# release s_barrier of every grid barrier sunk below the next phase's ALU-only prologue (re-inserted on every exit edge) so the waiting waves run and instruction-cache-warm that code during the grid-bar
# speedup vs baseline: 1.0086x; 1.0086x over previous
.LBB0_89:
	s_or_b64 exec, exec, s[4:5]
	s_waitcnt lgkmcnt(0)
	v_mov_b32_e32 v0, 0
	s_cmpk_lt_i32 s70, 0x400
	v_mbcnt_lo_u32_b32 v0, -1, v0
	s_cselect_b64 s[14:15], -1, 0
	s_cmpk_gt_i32 s70, 0x3ff
	v_mbcnt_hi_u32_b32 v0, -1, v0
	s_cselect_b64 s[4:5], -1, 0
	v_add_u32_e32 v10, s33, v0
	v_writelane_b32 v255, s4, 20
	s_and_b64 vcc, exec, s[4:5]
	v_readfirstlane_b32 s3, v10
	v_writelane_b32 v255, s5, 21
	s_cbranch_vccz .LBB0_92
	s_and_b32 s1, s70, 0x7fffffc0
	s_mov_b64 s[6:7], 0
	s_cmpk_lg_i32 s1, 0x400
	s_mov_b64 s[4:5], 0
	s_cbranch_scc1 .LBB0_93
	s_bfe_u32 s16, s70, 0x20004
	s_and_b32 s18, s70, 15
	s_mov_b32 s38, 64
	s_mov_b64 s[4:5], -1
	s_branch .LBB0_93

.LBB0_99:
	s_add_u32 s6, s82, 0x34ff7300
	s_addc_u32 s7, s83, 0
	v_writelane_b32 v255, s6, 22
	s_add_u32 s1, s82, 0x351ff300
	s_addc_u32 s88, s83, 0
	v_writelane_b32 v255, s7, 23
	v_writelane_b32 v255, s1, 24
	s_andn2_b64 vcc, exec, s[4:5]
	s_cbranch_vccz .Lmy_bsk1
	s_barrier
	s_branch .LBB0_184
.Lmy_bsk1:
	s_ashr_i32 s20, s3, 8
	s_lshl_b32 s2, s20, 6
	s_cmp_lg_u32 s38, 64
	s_cselect_b64 s[8:9], -1, 0
	s_cmp_eq_u32 s38, 64
	s_cselect_b64 s[4:5], -1, 0
	s_and_b64 vcc, s[4:5], exec
	s_cselect_b32 s1, 4, 16
	s_lshl_b32 s6, s38, 8
	v_and_b32_e32 v11, 15, v10
	s_add_i32 s6, s6, s2
	v_or_b32_e32 v0, s6, v11
	v_ashrrev_i32_e32 v1, 31, v0
	v_lshl_add_u64 v[0:1], v[0:1], 2, s[10:11]
	s_barrier
	global_load_dword v244, v[0:1], off
	global_load_dword v243, v[0:1], off offset:64
	global_load_dword v242, v[0:1], off offset:128
	global_load_dword v241, v[0:1], off offset:192
	v_mov_b32_e32 v239, 1.0
	v_mov_b32_e32 v240, 1.0
	s_cbranch_vccnz .LBB0_104
	global_load_dword v240, v[0:1], off offset:512
	v_cndmask_b32_e64 v2, 0, 1, s[8:9]
	v_cmp_ne_u32_e64 s[6:7], 1, v2
	s_andn2_b64 vcc, exec, s[8:9]
	s_cbranch_vccz .LBB0_105

.LBB0_236:
	v_writelane_b32 v255, s74, 26
	s_nop 1
	v_writelane_b32 v255, s75, 27
	v_writelane_b32 v255, s72, 28
	s_nop 1
	v_writelane_b32 v255, s73, 29
	v_writelane_b32 v255, s68, 30
	s_or_b64 exec, exec, s[4:5]
	s_waitcnt lgkmcnt(0)
	v_mov_b32_e32 v0, 0
	s_mov_b32 s84, s70
	v_mbcnt_lo_u32_b32 v0, -1, v0
	v_mbcnt_hi_u32_b32 v0, -1, v0
	v_add_u32_e32 v97, s33, v0
	v_cndmask_b32_e64 v0, 0, 1, s[14:15]
	v_readfirstlane_b32 s1, v97
	s_ashr_i32 s89, s1, 6
	s_add_u32 s2, s82, 0xdae7300
	v_writelane_b32 v255, s2, 31
	s_addc_u32 s2, s83, 0
	v_writelane_b32 v255, s2, 33
	s_add_u32 s2, s82, 0x11be7300
	v_writelane_b32 v255, s2, 35
	s_addc_u32 s2, s83, 0
	v_writelane_b32 v255, s2, 37
	s_mov_b32 s2, 0
	s_ashr_i32 s3, s2, 31
	s_lshl_b64 s[2:3], s[2:3], 3
	v_readlane_b32 s6, v255, 2
	v_readlane_b32 s7, v255, 3
	s_add_u32 s2, s6, s2
	s_addc_u32 s3, s7, s3
	s_barrier
	s_load_dwordx2 s[2:3], s[2:3], 0x38
	s_mov_b32 s5, 0
	v_mov_b32_e32 v67, 0
	v_and_b32_e32 v96, 63, v97
	v_lshlrev_b32_e32 v64, 3, v97
	s_waitcnt lgkmcnt(0)
	v_writelane_b32 v255, s2, 39
	s_nop 1
	v_writelane_b32 v255, s3, 40
	s_mov_b32 s2, 0
	s_ashr_i32 s3, s2, 31
	s_lshl_b64 s[2:3], s[2:3], 3
	s_add_u32 s2, s6, s2
	s_addc_u32 s3, s7, s3
	s_load_dwordx2 s[2:3], s[2:3], 0x40
	s_waitcnt lgkmcnt(0)
	v_writelane_b32 v255, s2, 41
	s_nop 1
	v_writelane_b32 v255, s3, 42
	s_mov_b32 s2, 0
	s_ashr_i32 s3, s2, 31
	s_lshl_b64 s[2:3], s[2:3], 3
	s_add_u32 s2, s6, s2
	s_addc_u32 s3, s7, s3
	s_load_dwordx2 s[96:97], s[2:3], 0x48
	v_cmp_ne_u32_e64 s[2:3], 1, v0
	s_andn2_b64 vcc, exec, s[14:15]
	s_nop 0
	v_writelane_b32 v255, s2, 43
	s_nop 1
	v_writelane_b32 v255, s3, 44
	s_cbranch_vccnz .LBB0_305
	v_and_b32_e32 v0, 3, v97
	v_lshlrev_b32_e32 v5, 5, v0
	v_lshlrev_b32_e32 v66, 7, v0
	v_lshlrev_b32_e32 v9, 2, v0
	v_lshrrev_b32_e32 v0, 3, v97
	s_lshl_b32 s3, s89, 2
	v_and_b32_e32 v0, 2, v0
	v_bfe_u32 v2, v97, 1, 1
	v_bfe_u32 v3, v97, 2, 2
	v_or3_b32 v0, s3, v0, v2
	s_movk_i32 s2, 0x80
	v_lshlrev_b32_e32 v2, 6, v3
	v_lshlrev_b32_e32 v0, 4, v0
	v_cmp_gt_i32_e32 vcc, s2, v97
	s_add_i32 s2, 0, 0x18000
	v_xad_u32 v13, v0, v2, 0
	v_lshlrev_b32_e32 v0, 8, v97
	v_lshl_add_u32 v98, v97, 2, s2
	v_ashrrev_i32_e32 v68, 2, v97
	v_add_u32_e32 v99, s2, v66
	s_add_i32 s2, 0, 0x10000
	v_and_b32_e32 v0, 0x1f00, v0
	v_readlane_b32 s6, v255, 41
	v_lshl_add_u32 v7, v68, 8, s2
	v_add_u32_e32 v16, s2, v0
	s_lshl_b32 s2, s89, 5
	v_readlane_b32 s7, v255, 42
	s_ashr_i32 s3, s2, 31
	v_readlane_b32 s4, v255, 31
	v_lshl_add_u64 v[70:71], s[6:7], 0, v[66:67]
	s_lshl_b64 s[6:7], s[2:3], 1
	v_lshrrev_b32_e32 v1, 5, v96
	s_add_u32 s6, s4, s6
	v_readlane_b32 s4, v255, 33
	s_addc_u32 s7, s4, s7
	v_lshlrev_b32_e32 v66, 3, v1
	v_lshl_add_u64 v[72:73], s[6:7], 0, v[66:67]
	s_lshl_b64 s[2:3], s[2:3], 2
	v_readlane_b32 s6, v255, 39
	v_or_b32_e32 v19, 8, v5
	v_or_b32_e32 v20, 16, v5
	v_readlane_b32 s7, v255, 40
	s_add_u32 s2, s6, s2
	v_cmp_le_i32_e64 s[24:25], v19, v68
	v_or_b32_e32 v19, 9, v5
	v_cmp_le_i32_e64 s[42:43], v20, v68
	v_or_b32_e32 v20, 17, v5
	v_or_b32_e32 v21, 24, v5
	s_addc_u32 s3, s7, s3
	s_add_i32 s6, s89, 32
	v_or_b32_e32 v18, 2, v5
	v_cmp_le_i32_e64 s[26:27], v19, v68
	v_or_b32_e32 v19, 10, v5
	v_cmp_le_i32_e64 s[44:45], v20, v68
	v_or_b32_e32 v20, 18, v5
	v_cmp_le_i32_e64 s[58:59], v21, v68
	v_or_b32_e32 v21, 25, v5
	v_lshl_or_b32 v8, s6, 6, v96
	s_lshl_b32 s8, s6, 10
	s_add_i32 s6, s89, 40
	v_cmp_le_i32_e64 s[12:13], v18, v68
	v_or_b32_e32 v18, 3, v5
	v_cmp_le_i32_e64 s[28:29], v19, v68
	v_or_b32_e32 v19, 11, v5
	v_cmp_le_i32_e64 s[46:47], v20, v68
	v_or_b32_e32 v20, 19, v5
	v_cmp_le_i32_e64 s[60:61], v21, v68
	v_or_b32_e32 v21, 26, v5
	v_lshlrev_b32_e32 v66, 4, v1
	v_lshl_or_b32 v10, s6, 6, v96
	s_lshl_b32 s9, s6, 10
	s_add_i32 s6, s89, 48
	v_cmp_le_i32_e64 s[14:15], v18, v68
	v_or_b32_e32 v18, 4, v5
	v_cmp_le_i32_e64 s[30:31], v19, v68
	v_or_b32_e32 v19, 12, v5
	v_cmp_le_i32_e64 s[48:49], v20, v68
	v_or_b32_e32 v20, 20, v5
	v_cmp_le_i32_e64 s[62:63], v21, v68
	v_or_b32_e32 v21, 27, v5
	v_lshl_add_u64 v[74:75], s[2:3], 0, v[66:67]
	s_andn2_b32 s1, s1, 63
	s_add_i32 s2, s89, 8
	s_add_i32 s3, s89, 16
	s_add_i32 s4, s89, 24
	v_lshl_or_b32 v12, s6, 6, v96
	s_lshl_b32 s74, s6, 10
	s_add_i32 s6, s89, 56
	v_cmp_le_i32_e64 s[16:17], v18, v68
	v_or_b32_e32 v18, 5, v5
	v_cmp_le_i32_e64 s[34:35], v19, v68
	v_or_b32_e32 v19, 13, v5
	v_cmp_le_i32_e64 s[50:51], v20, v68
	v_or_b32_e32 v20, 21, v5
	v_cmp_le_i32_e64 s[64:65], v21, v68
	v_or_b32_e32 v21, 28, v5
	v_or_b32_e32 v0, s1, v96
	v_lshl_or_b32 v2, s2, 6, v96
	v_lshl_or_b32 v4, s3, 6, v96
	v_lshl_or_b32 v6, s4, 6, v96
	v_lshl_or_b32 v14, s6, 6, v96
	v_cmp_le_i32_e64 s[18:19], v18, v68
	v_or_b32_e32 v18, 6, v5
	v_cmp_le_i32_e64 s[36:37], v19, v68
	v_or_b32_e32 v19, 14, v5
	v_cmp_le_i32_e64 s[52:53], v20, v68
	v_or_b32_e32 v20, 22, v5
	v_cmp_le_i32_e64 s[66:67], v21, v68
	v_or_b32_e32 v21, 29, v5
	v_and_b32_e32 v11, 15, v68
	v_ashrrev_i32_e32 v100, 5, v0
	v_ashrrev_i32_e32 v101, 5, v2
	v_ashrrev_i32_e32 v102, 5, v4
	v_ashrrev_i32_e32 v103, 5, v6
	v_ashrrev_i32_e32 v104, 5, v8
	v_ashrrev_i32_e32 v105, 5, v10
	v_ashrrev_i32_e32 v106, 5, v12
	v_ashrrev_i32_e32 v107, 5, v14
	s_lshl_b32 s75, s6, 10
	v_cmp_le_i32_e64 s[6:7], v5, v68
	v_cmp_lt_i32_e64 s[10:11], v5, v68
	v_cmp_le_i32_e64 s[20:21], v18, v68
	v_or_b32_e32 v18, 7, v5
	v_cmp_le_i32_e64 s[38:39], v19, v68
	v_or_b32_e32 v19, 15, v5
	v_cmp_le_i32_e64 s[54:55], v20, v68
	v_or_b32_e32 v20, 23, v5
	v_cmp_le_i32_e64 s[68:69], v21, v68
	v_or_b32_e32 v21, 30, v5
	v_or_b32_e32 v5, 31, v5
	v_and_b32_e32 v65, 31, v97
	v_and_b32_e32 v15, 8, v64
	v_and_b32_e32 v17, 15, v97
	v_lshlrev_b32_e32 v0, 2, v100
	v_lshlrev_b32_e32 v2, 2, v101
	v_lshlrev_b32_e32 v4, 2, v102
	v_lshlrev_b32_e32 v6, 2, v103
	v_lshlrev_b32_e32 v8, 2, v104
	v_lshlrev_b32_e32 v10, 2, v105
	v_lshlrev_b32_e32 v12, 2, v106
	v_lshlrev_b32_e32 v14, 2, v107
	v_cmp_le_i32_e64 s[22:23], v18, v68
	v_bitop3_b32 v18, v9, v68, 15 bitop3:0x78
	v_cmp_le_i32_e64 s[40:41], v19, v68
	v_bitop3_b32 v19, v9, v11, 1 bitop3:0x36
	v_cmp_le_i32_e64 s[56:57], v20, v68
	v_bitop3_b32 v20, v9, v11, 2 bitop3:0x36
	v_cmp_le_i32_e64 s[72:73], v5, v68
	v_bitop3_b32 v5, v9, v11, 3 bitop3:0x36
	v_lshlrev_b32_e32 v9, 12, v1
	v_bitop3_b32 v0, v0, v65, 12 bitop3:0x6c
	v_bitop3_b32 v2, v2, v65, 12 bitop3:0x6c
	v_bitop3_b32 v4, v4, v65, 12 bitop3:0x6c
	v_bitop3_b32 v6, v6, v65, 12 bitop3:0x6c
	v_bitop3_b32 v8, v8, v65, 12 bitop3:0x6c
	v_bitop3_b32 v10, v10, v65, 12 bitop3:0x6c
	v_bitop3_b32 v12, v12, v65, 12 bitop3:0x6c
	v_bitop3_b32 v14, v14, v65, 12 bitop3:0x6c
	v_cmp_le_i32_e64 s[70:71], v21, v68
	v_add3_u32 v9, v13, v15, v9
	v_bitop3_b32 v11, v1, v97, 15 bitop3:0x78
	v_bitop3_b32 v13, v1, v17, 2 bitop3:0x36
	v_bitop3_b32 v15, v1, v17, 4 bitop3:0x36
	v_bitop3_b32 v21, v1, v17, 6 bitop3:0x36
	v_bitop3_b32 v22, v1, v17, 8 bitop3:0x36
	v_bitop3_b32 v23, v1, v17, 10 bitop3:0x36
	v_bitop3_b32 v24, v1, v17, 12 bitop3:0x36
	v_bitop3_b32 v1, v1, v17, 14 bitop3:0x36
	v_lshlrev_b32_e32 v0, 3, v0
	s_lshl_b32 s1, s89, 10
	v_lshlrev_b32_e32 v2, 3, v2
	s_lshl_b32 s2, s2, 10
	v_lshlrev_b32_e32 v4, 3, v4
	s_lshl_b32 s3, s3, 10
	v_lshlrev_b32_e32 v6, 3, v6
	s_lshl_b32 s4, s4, 10
	v_lshlrev_b32_e32 v8, 3, v8
	v_lshlrev_b32_e32 v10, 3, v10
	v_lshlrev_b32_e32 v12, 3, v12
	v_lshlrev_b32_e32 v14, 3, v14
	v_lshlrev_b32_e32 v18, 4, v18
	v_lshlrev_b32_e32 v19, 4, v19
	v_lshlrev_b32_e32 v20, 4, v20
	v_lshlrev_b32_e32 v5, 4, v5
	v_lshlrev_b32_e32 v3, 9, v3
	v_lshlrev_b32_e32 v11, 4, v11
	v_lshlrev_b32_e32 v13, 4, v13
	v_lshlrev_b32_e32 v15, 4, v15
	v_lshlrev_b32_e32 v21, 4, v21
	v_lshlrev_b32_e32 v22, 4, v22
	v_lshlrev_b32_e32 v23, 4, v23
	v_lshlrev_b32_e32 v24, 4, v24
	v_lshlrev_b32_e32 v1, 4, v1
	v_ashrrev_i32_e32 v69, 31, v68
	v_or_b32_e32 v108, 32, v65
	v_or_b32_e32 v109, 64, v65
	v_or_b32_e32 v110, 0x60, v65
	s_lshl_b32 s85, s84, 4
	s_lshl_b32 s92, s0, 4
	v_lshlrev_b32_e32 v76, 1, v0
	s_add_i32 s93, s1, 0
	v_lshlrev_b32_e32 v66, 1, v2
	s_add_i32 s94, s2, 0
	v_lshlrev_b32_e32 v78, 1, v4
	s_add_i32 s95, s3, 0
	v_lshlrev_b32_e32 v80, 1, v6
	s_add_i32 s78, s4, 0
	v_lshlrev_b32_e32 v82, 1, v8
	s_add_i32 s79, s8, 0
	v_lshlrev_b32_e32 v84, 1, v10
	s_add_i32 s3, s9, 0
	v_lshlrev_b32_e32 v86, 1, v12
	s_add_i32 s76, s74, 0
	v_lshlrev_b32_e32 v88, 1, v14
	s_add_i32 s77, s75, 0
	v_mov_b32_e32 v111, 0x358637bd
	v_add_u32_e32 v112, v7, v18
	v_add_u32_e32 v113, v7, v19
	v_add_u32_e32 v114, v7, v20
	v_add_u32_e32 v115, v7, v5
	v_add_u32_e32 v116, v9, v3
	v_add_u32_e32 v117, v16, v11
	v_add_u32_e32 v118, v16, v13
	v_add_u32_e32 v119, v16, v15
	v_add_u32_e32 v120, v16, v21
	v_add_u32_e32 v121, v16, v22
	v_add_u32_e32 v122, v16, v23
	v_add_u32_e32 v123, v16, v24
	v_add_u32_e32 v124, v16, v1
	v_mov_b32_e32 v77, v67
	s_mov_b32 s90, s84
	s_branch .LBB0_239

.LBB0_362:
	s_or_b64 exec, exec, s[4:5]
	s_waitcnt lgkmcnt(0)
	v_mov_b32_e32 v0, 0
	v_readlane_b32 s4, v255, 16
	v_mbcnt_lo_u32_b32 v0, -1, v0
	v_mbcnt_hi_u32_b32 v0, -1, v0
	v_add_u32_e32 v1, s33, v0
	v_readlane_b32 s5, v255, 17
	s_and_b64 vcc, exec, s[4:5]
	v_readfirstlane_b32 s3, v1
	s_cbranch_vccz .LBB0_365
	s_and_b32 s1, s66, 0x7fffffe0
	s_mov_b64 s[12:13], 0
	s_cmpk_lg_i32 s1, 0x100
	s_mov_b64 s[6:7], 0
	s_cbranch_scc1 .LBB0_366
	s_bfe_u32 s4, s66, 0x30002
	s_and_b32 s8, s66, 3
	s_mov_b32 s10, 64
	s_mov_b64 s[6:7], -1
	s_branch .LBB0_366

.LBB0_372:
	s_add_u32 s12, s82, 0x34a77300
	s_addc_u32 s13, s83, 0
	v_writelane_b32 v255, s12, 39
	s_andn2_b64 vcc, exec, s[6:7]
	s_nop 0
	v_writelane_b32 v255, s13, 40
	s_cbranch_vccz .Lmy_bsk2
	s_barrier
	s_branch .LBB0_425
.Lmy_bsk2:
	v_ashrrev_i32_e32 v2, 31, v1
	v_lshrrev_b32_e32 v2, 26, v2
	v_add_u32_e32 v2, v1, v2
	v_ashrrev_i32_e32 v10, 6, v2
	v_bfe_i32 v2, v1, 27, 1
	v_lshlrev_b32_e32 v0, 4, v1
	v_lshrrev_b32_e32 v2, 22, v2
	v_add_u32_e32 v2, v0, v2
	v_and_b32_e32 v2, 0xfffffc00, v2
	v_sub_u32_e32 v2, v0, v2
	v_lshrrev_b32_e32 v3, 4, v2
	v_bitop3_b32 v3, v3, v2, 32 bitop3:0x6c
	v_ashrrev_i32_e32 v2, 31, v2
	v_lshrrev_b32_e32 v2, 26, v2
	v_add_u32_e32 v2, v3, v2
	v_ashrrev_i32_e32 v11, 6, v2
	v_lshlrev_b32_e32 v4, 3, v10
	v_mul_i32_i24_e32 v5, 64, v11
	v_and_b32_e32 v4, -16, v4
	v_sub_u32_e32 v3, v3, v5
	v_mov_b32_e32 v5, 1
	v_add_u32_e32 v2, v11, v4
	v_lshlrev_b32_e32 v4, 5, v10
	v_ashrrev_i16_sdwa v3, v5, sext(v3) dst_sel:DWORD dst_unused:UNUSED_PAD src0_sel:DWORD src1_sel:BYTE_0
	v_and_b32_e32 v4, 32, v4
	v_bfe_i32 v12, v3, 0, 16
	v_and_b32_e32 v7, 3, v11
	s_mov_b32 s1, 0xfffe0
	v_add_lshl_u32 v4, v4, v12, 1
	v_add_u32_e32 v0, 0x2000, v0
	v_lshlrev_b32_e32 v3, 1, v2
	v_lshrrev_b32_e32 v6, 2, v2
	v_and_or_b32 v7, v2, s1, v7
	v_lshl_add_u32 v196, v2, 12, v4
	v_ashrrev_i32_e32 v2, 31, v0
	v_lshrrev_b32_e32 v2, 22, v2
	v_add_u32_e32 v2, v0, v2
	v_ashrrev_i32_e32 v13, 10, v2
	v_mul_i32_i24_e32 v2, 0x400, v13
	v_sub_u32_e32 v0, v0, v2
	v_and_b32_e32 v3, 24, v3
	v_and_b32_e32 v6, 4, v6
	v_lshrrev_b32_e32 v2, 4, v0
	v_or3_b32 v3, v7, v6, v3
	v_bitop3_b32 v0, v2, v0, 32 bitop3:0x6c
	v_lshl_add_u32 v198, v3, 12, v4
	v_ashrrev_i32_e32 v3, 31, v0
	s_ashr_i32 s2, s3, 6
	v_lshrrev_b32_e32 v3, 26, v3
	v_add_u32_e32 v3, v0, v3
	s_ashr_i32 s6, s3, 8
	s_lshl_b32 s38, s2, 10
	v_lshlrev_b32_e32 v2, 3, v13
	v_ashrrev_i32_e32 v14, 6, v3
	v_and_b32_e32 v3, 0xc0, v3
	s_cmp_eq_u32 s10, 64
	v_and_b32_e32 v2, -16, v2
	v_sub_u32_e32 v0, v0, v3
	s_cselect_b64 s[12:13], -1, 0
	v_add_u32_e32 v2, v14, v2
	v_ashrrev_i16_sdwa v0, v5, sext(v0) dst_sel:DWORD dst_unused:UNUSED_PAD src0_sel:DWORD src1_sel:BYTE_0
	v_and_b32_e32 v5, 3, v14
	s_and_b64 s[14:15], s[12:13], exec
	v_and_or_b32 v5, v2, s1, v5
	s_cselect_b32 s1, 4, 32
	s_ashr_i32 s5, s4, 31
	s_ashr_i32 s9, s8, 31
	s_ashr_i32 s11, s10, 31
	s_lshl_b64 s[14:15], s[4:5], 9
	s_lshl_b64 s[16:17], s[8:9], 20
	s_add_u32 s5, s86, s16
	s_addc_u32 s7, s87, s17
	s_add_u32 s34, s5, s14
	s_addc_u32 s35, s7, s15
	s_add_i32 s9, s38, 0
	s_add_i32 m0, s9, 0x10000
	s_lshl_b64 s[16:17], s[10:11], 20
	s_barrier
	global_load_lds_dwordx4 v198, s[34:35]
	s_add_i32 m0, s9, 0x12000
	v_lshlrev_b32_e32 v4, 5, v13
	v_bfe_i32 v15, v0, 0, 16
	v_lshlrev_b32_e32 v0, 1, v2
	v_lshrrev_b32_e32 v3, 2, v2
	s_add_u32 s5, s58, s16
	v_and_b32_e32 v4, 32, v4
	v_and_b32_e32 v0, 24, v0
	v_and_b32_e32 v3, 4, v3
	s_addc_u32 s7, s59, s17
	v_or3_b32 v0, v5, v3, v0
	v_add_lshl_u32 v3, v4, v15, 1
	s_add_u32 s30, s5, s14
	v_lshl_add_u32 v202, v0, 12, v3
	s_addc_u32 s31, s7, s15
	s_add_i32 s39, s9, 0x2000
	global_load_lds_dwordx4 v202, s[34:35]
	s_mov_b32 m0, s9
	s_add_u32 s14, s34, 0x80000
	v_lshl_add_u32 v200, v2, 12, v3
	global_load_lds_dwordx4 v196, s[30:31]
	s_mov_b32 m0, s39
	s_addc_u32 s15, s35, 0
	s_add_i32 s40, s9, 0x14000
	global_load_lds_dwordx4 v200, s[30:31]
	s_mov_b32 m0, s40
	s_add_i32 s41, s9, 0x16000
	global_load_lds_dwordx4 v198, s[14:15]
	s_mov_b32 m0, s41
	v_mov_b32_e32 v0, 0
	global_load_lds_dwordx4 v202, s[14:15]
	s_add_u32 s14, s30, 0x80000
	s_addc_u32 s15, s31, 0
	s_add_i32 s42, s9, 0x4000
	s_mov_b32 m0, s42
	s_add_i32 s43, s9, 0x6000
	global_load_lds_dwordx4 v196, s[14:15]
	s_mov_b32 m0, s43
	v_mov_b32_e32 v199, v0
	global_load_lds_dwordx4 v200, s[14:15]
	v_mov_b32_e32 v203, v0
	v_mov_b32_e32 v197, v0
	v_mov_b32_e32 v201, v0
	s_mov_b32 s11, 0
	v_lshl_add_u64 v[8:9], s[34:35], 0, v[198:199]
	v_lshl_add_u64 v[6:7], s[34:35], 0, v[202:203]
	v_lshl_add_u64 v[4:5], s[30:31], 0, v[196:197]
	s_cmp_lg_u32 s6, 1
	v_lshl_add_u64 v[2:3], s[30:31], 0, v[200:201]
	s_cbranch_scc1 .LBB0_375
	s_barrier

.LBB0_484:
	s_or_b64 exec, exec, s[4:5]
	s_waitcnt lgkmcnt(0)
	v_mov_b32_e32 v0, 0
	v_mov_b32_e32 v21, 0
	v_mbcnt_lo_u32_b32 v0, -1, v0
	v_mbcnt_hi_u32_b32 v0, -1, v0
	v_add_u32_e32 v20, s33, v0
	s_nop 0
	v_readfirstlane_b32 s1, v20
	s_ashr_i32 s2, s1, 6
	v_readlane_b32 s1, v255, 13
	s_add_i32 s1, s2, s1
	s_cmpk_gt_i32 s1, 0x7f
	s_cbranch_scc0 .Lmy_bsk3
	s_barrier
	s_branch .LBB0_489
.Lmy_bsk3:
	v_readlane_b32 s8, v255, 13
	s_lshl_b32 s4, s0, 3
	s_ashr_i32 s3, s2, 31
	s_ashr_i32 s5, s8, 31
	s_add_u32 s10, s2, s8
	s_addc_u32 s11, s3, s5
	s_lshl_b64 s[2:3], s[10:11], 2
	s_add_u32 s2, s2, 0x23e00
	s_addc_u32 s3, s3, 0
	s_add_i32 s12, s1, 0x4000
	v_and_b32_e32 v2, 63, v20
	s_ashr_i32 s13, s12, 31
	v_lshlrev_b32_e32 v0, 2, v2
	s_ashr_i32 s5, s4, 31
	s_lshl_b64 s[10:11], s[10:11], 12
	s_lshl_b64 s[12:13], s[12:13], 11
	v_cmp_eq_u32_e64 s[6:7], 0, v2
	v_xor_b32_e32 v22, 0x80, v0
	v_xor_b32_e32 v23, 64, v0
	v_xor_b32_e32 v24, 32, v0
	v_xor_b32_e32 v25, 16, v0
	v_xor_b32_e32 v26, 8, v0
	v_xor_b32_e32 v27, 4, v0
	s_lshl_b64 s[8:9], s[4:5], 2
	v_lshl_or_b32 v0, v2, 4, s10
	v_mov_b32_e32 v1, s11
	s_lshl_b64 s[10:11], s[4:5], 12
	v_lshl_or_b32 v2, v2, 3, s12
	v_mov_b32_e32 v3, s13
	s_lshl_b64 s[12:13], s[4:5], 11
	s_barrier
	s_branch .LBB0_487

.LBB0_544:
	s_or_b64 exec, exec, s[4:5]
	s_waitcnt lgkmcnt(0)
	v_mov_b32_e32 v0, 0
	s_cmpk_lt_i32 s66, 0x596
	v_mbcnt_lo_u32_b32 v0, -1, v0
	v_mbcnt_hi_u32_b32 v0, -1, v0
	v_add_u32_e32 v10, s33, v0
	s_cselect_b64 s[4:5], -1, 0
	s_cmpk_gt_i32 s66, 0x595
	v_readfirstlane_b32 s3, v10
	s_cbranch_scc1 .LBB0_550
	s_ashr_i32 s1, s66, 31
	s_lshr_b32 s1, s1, 29
	s_add_i32 s1, s66, s1
	s_and_b32 s2, s1, -8
	s_sub_i32 s2, s66, s2
	s_cmp_gt_i32 s2, 5
	s_cbranch_scc0 .LBB0_547
	s_mul_i32 s6, s2, 0xb2
	s_add_i32 s8, s6, 6
	s_cbranch_execz .LBB0_548
	s_branch .LBB0_549

.LBB0_550:
	s_add_u32 s6, s82, 0x15ce7300
	s_addc_u32 s7, s83, 0
	v_writelane_b32 v255, s6, 18
	v_cndmask_b32_e64 v0, 0, 1, s[4:5]
	s_andn2_b64 vcc, exec, s[4:5]
	v_writelane_b32 v255, s7, 19
	v_cmp_ne_u32_e64 s[6:7], 1, v0
	s_nop 1
	v_writelane_b32 v255, s6, 41
	s_nop 1
	v_writelane_b32 v255, s7, 42
	s_cbranch_vccz .Lmy_bsk4
	s_barrier
	s_branch .LBB0_596
.Lmy_bsk4:
	s_ashr_i32 s8, s3, 8
	s_lshl_b32 s2, s8, 6
	s_add_u32 s4, s82, 0x13e00
	s_addc_u32 s5, s83, 0
	s_cmp_eq_u32 s20, 64
	s_cselect_b64 s[14:15], -1, 0
	s_cmp_lg_u32 s20, 64
	s_cselect_b64 s[6:7], -1, 0
	s_lshl_b32 s9, s20, 8
	v_and_b32_e32 v11, 15, v10
	s_add_i32 s9, s9, s2
	v_or_b32_e32 v0, s9, v11
	v_ashrrev_i32_e32 v1, 31, v0
	s_mov_b32 s1, 16
	v_lshl_add_u64 v[0:1], v[0:1], 2, s[4:5]
	s_barrier
	global_load_dword v233, v[0:1], off
	global_load_dword v232, v[0:1], off offset:64
	global_load_dword v231, v[0:1], off offset:128
	global_load_dword v230, v[0:1], off offset:192
	v_mov_b32_e32 v228, 1.0
	s_and_b64 vcc, exec, s[14:15]
	v_mov_b32_e32 v229, 1.0
	s_cbranch_vccnz .LBB0_555
	global_load_dword v229, v[0:1], off offset:512
	v_cndmask_b32_e64 v2, 0, 1, s[6:7]
	v_cmp_ne_u32_e64 s[12:13], 1, v2
	s_andn2_b64 vcc, exec, s[6:7]
	s_cbranch_vccz .LBB0_556

.LBB0_657:
	s_or_b64 exec, exec, s[4:5]
	s_waitcnt lgkmcnt(0)
	v_mov_b32_e32 v0, 0
	v_readlane_b32 s4, v255, 16
	v_mbcnt_lo_u32_b32 v0, -1, v0
	v_mbcnt_hi_u32_b32 v0, -1, v0
	v_add_u32_e32 v1, s33, v0
	v_readlane_b32 s5, v255, 17
	s_and_b64 vcc, exec, s[4:5]
	v_readfirstlane_b32 s3, v1
	s_cbranch_vccz .LBB0_660
	s_mov_b64 s[8:9], 0
	s_cmpk_gt_u32 s66, 0x12b
	s_mov_b64 s[6:7], 0
	s_cbranch_scc1 .LBB0_661
	s_and_b32 s31, s66, 3
	s_bfe_u32 s4, s66, 0x40002
	s_mov_b32 s1, 64
	s_mov_b64 s[6:7], -1
	s_branch .LBB0_661

.LBB0_667:
	s_andn2_b64 vcc, exec, s[6:7]
	s_cbranch_vccz .Lmy_bsk5
	s_barrier
	s_branch .LBB0_724
.Lmy_bsk5:
	v_ashrrev_i32_e32 v2, 31, v1
	v_lshrrev_b32_e32 v2, 26, v2
	v_add_u32_e32 v2, v1, v2
	v_ashrrev_i32_e32 v10, 6, v2
	v_bfe_i32 v2, v1, 27, 1
	v_lshlrev_b32_e32 v0, 4, v1
	v_lshrrev_b32_e32 v2, 22, v2
	v_add_u32_e32 v2, v0, v2
	v_and_b32_e32 v2, 0xfffffc00, v2
	v_sub_u32_e32 v2, v0, v2
	v_lshrrev_b32_e32 v3, 4, v2
	v_bitop3_b32 v3, v3, v2, 32 bitop3:0x6c
	v_ashrrev_i32_e32 v2, 31, v2
	v_lshrrev_b32_e32 v2, 26, v2
	v_lshlrev_b32_e32 v4, 3, v10
	v_add_u32_e32 v2, v3, v2
	v_and_b32_e32 v4, -16, v4
	v_ashrrev_i32_e32 v12, 6, v2
	v_add_u32_e32 v2, v12, v4
	v_lshlrev_b32_e32 v4, 5, v10
	v_and_b32_e32 v11, 32, v4
	v_mul_i32_i24_e32 v4, 64, v12
	v_sub_u32_e32 v3, v3, v4
	v_mov_b32_e32 v4, 1
	v_ashrrev_i16_sdwa v3, v4, sext(v3) dst_sel:DWORD dst_unused:UNUSED_PAD src0_sel:DWORD src1_sel:BYTE_0
	v_lshlrev_b32_e32 v5, 1, v2
	v_lshrrev_b32_e32 v6, 2, v2
	v_and_b32_e32 v7, 3, v12
	s_mov_b32 s2, 0xffffe0
	v_bfe_i32 v13, v3, 0, 16
	v_and_b32_e32 v5, 24, v5
	v_and_b32_e32 v6, 4, v6
	v_and_or_b32 v7, v2, s2, v7
	s_movk_i32 s6, 0xb00
	v_add_u32_e32 v3, v11, v13
	v_or3_b32 v5, v7, v6, v5
	v_mul_lo_u32 v2, v2, s6
	v_add_lshl_u32 v196, v3, v2, 1
	v_mul_u32_u24_e32 v2, 0xb00, v5
	v_add_u32_e32 v0, 0x2000, v0
	v_add_lshl_u32 v198, v2, v3, 1
	v_ashrrev_i32_e32 v2, 31, v0
	v_lshrrev_b32_e32 v2, 22, v2
	v_add_u32_e32 v2, v0, v2
	v_ashrrev_i32_e32 v14, 10, v2
	v_mul_i32_i24_e32 v2, 0x400, v14
	v_sub_u32_e32 v0, v0, v2
	v_lshrrev_b32_e32 v2, 4, v0
	v_bitop3_b32 v0, v2, v0, 32 bitop3:0x6c
	s_ashr_i32 s8, s3, 6
	v_ashrrev_i32_e32 v3, 31, v0
	v_lshrrev_b32_e32 v3, 26, v3
	s_ashr_i32 s10, s3, 8
	s_lshl_b32 s30, s8, 10
	v_lshlrev_b32_e32 v2, 3, v14
	v_add_u32_e32 v3, v0, v3
	s_cmp_eq_u32 s1, 64
	v_and_b32_e32 v2, -16, v2
	v_ashrrev_i32_e32 v15, 6, v3
	v_lshlrev_b32_e32 v5, 5, v14
	s_cselect_b64 s[16:17], -1, 0
	v_add_u32_e32 v2, v15, v2
	v_and_b32_e32 v16, 32, v5
	v_and_b32_e32 v5, 3, v15
	s_and_b64 s[12:13], s[16:17], exec
	v_and_or_b32 v5, v2, s2, v5
	s_cselect_b32 s2, 4, 44
	s_ashr_i32 s5, s4, 31
	s_lshl_b64 s[12:13], s[4:5], 9
	s_mul_i32 s7, s31, 0x160000
	s_mul_hi_i32 s5, s31, 0x160000
	s_add_u32 s7, s60, s7
	s_addc_u32 s5, s61, s5
	s_add_u32 s26, s7, s12
	v_and_b32_e32 v3, 0xc0, v3
	s_addc_u32 s27, s5, s13
	s_add_i32 s34, s30, 0
	v_sub_u32_e32 v0, v0, v3
	s_add_i32 m0, s34, 0x10000
	v_ashrrev_i16_sdwa v0, v4, sext(v0) dst_sel:DWORD dst_unused:UNUSED_PAD src0_sel:DWORD src1_sel:BYTE_0
	v_lshlrev_b32_e32 v3, 1, v2
	v_lshrrev_b32_e32 v4, 2, v2
	s_barrier
	global_load_lds_dwordx4 v198, s[26:27]
	s_add_i32 m0, s34, 0x12000
	s_mul_i32 s7, s1, 0x160000
	v_readlane_b32 s14, v255, 18
	v_bfe_i32 v17, v0, 0, 16
	v_and_b32_e32 v3, 24, v3
	v_and_b32_e32 v4, 4, v4
	s_mul_hi_i32 s5, s1, 0x160000
	v_readlane_b32 s15, v255, 19
	s_add_u32 s7, s14, s7
	v_add_u32_e32 v0, v16, v17
	v_or3_b32 v3, v5, v4, v3
	v_mul_lo_u32 v2, v2, s6
	s_addc_u32 s5, s15, s5
	v_add_lshl_u32 v200, v0, v2, 1
	v_mul_u32_u24_e32 v2, 0xb00, v3
	s_add_u32 s22, s7, s12
	v_add_lshl_u32 v202, v2, v0, 1
	s_addc_u32 s23, s5, s13
	s_add_i32 s35, s34, 0x2000
	global_load_lds_dwordx4 v202, s[26:27]
	s_mov_b32 m0, s34
	s_add_u32 s12, s26, 0xb0000
	global_load_lds_dwordx4 v196, s[22:23]
	s_mov_b32 m0, s35
	s_addc_u32 s13, s27, 0
	s_add_i32 s36, s34, 0x14000
	global_load_lds_dwordx4 v200, s[22:23]
	s_mov_b32 m0, s36
	s_add_i32 s37, s34, 0x16000
	global_load_lds_dwordx4 v198, s[12:13]
	s_mov_b32 m0, s37
	v_mov_b32_e32 v0, 0
	global_load_lds_dwordx4 v202, s[12:13]
	s_add_u32 s12, s22, 0xb0000
	s_addc_u32 s13, s23, 0
	s_add_i32 s38, s34, 0x4000
	s_mov_b32 m0, s38
	s_add_i32 s39, s34, 0x6000
	global_load_lds_dwordx4 v196, s[12:13]
	s_mov_b32 m0, s39
	v_mov_b32_e32 v199, v0
	global_load_lds_dwordx4 v200, s[12:13]
	v_mov_b32_e32 v203, v0
	v_mov_b32_e32 v197, v0
	v_mov_b32_e32 v201, v0
	s_mov_b32 s7, 0
	v_lshl_add_u64 v[8:9], s[26:27], 0, v[198:199]
	v_lshl_add_u64 v[6:7], s[26:27], 0, v[202:203]
	v_lshl_add_u64 v[4:5], s[22:23], 0, v[196:197]
	s_cmp_lg_u32 s10, 1
	v_lshl_add_u64 v[2:3], s[22:23], 0, v[200:201]
	s_cbranch_scc1 .LBB0_670
	s_barrier

.LBB0_785:
	s_or_b64 exec, exec, s[4:5]
	s_waitcnt lgkmcnt(0)
	v_mov_b32_e32 v0, 0
	v_mov_b32_e32 v33, 0
	v_mbcnt_lo_u32_b32 v0, -1, v0
	v_mbcnt_hi_u32_b32 v0, -1, v0
	v_add_u32_e32 v32, s33, v0
	s_nop 0
	v_readfirstlane_b32 s1, v32
	s_ashr_i32 s2, s1, 6
	v_readlane_b32 s1, v255, 13
	s_add_i32 s1, s2, s1
	s_cmpk_gt_i32 s1, 0x7f
	s_cbranch_scc0 .Lmy_bsk6
	s_barrier
	s_branch .LBB0_790
.Lmy_bsk6:
	v_readlane_b32 s6, v255, 13
	s_lshl_b32 s4, s0, 3
	s_ashr_i32 s3, s2, 31
	s_ashr_i32 s5, s6, 31
	s_add_u32 s8, s2, s6
	s_addc_u32 s9, s3, s5
	s_lshl_b64 s[2:3], s[8:9], 2
	s_add_u32 s2, s2, 0x34200
	s_addc_u32 s3, s3, 0
	s_add_i32 s10, s1, 0x4000
	v_and_b32_e32 v2, 63, v32
	s_ashr_i32 s11, s10, 31
	v_lshlrev_b32_e32 v0, 2, v2
	s_ashr_i32 s5, s4, 31
	s_lshl_b64 s[8:9], s[8:9], 12
	s_lshl_b64 s[10:11], s[10:11], 11
	v_cmp_eq_u32_e64 s[12:13], 0, v2
	v_xor_b32_e32 v34, 0x80, v0
	v_xor_b32_e32 v35, 64, v0
	v_xor_b32_e32 v36, 32, v0
	v_xor_b32_e32 v37, 16, v0
	v_xor_b32_e32 v38, 8, v0
	v_xor_b32_e32 v39, 4, v0
	s_lshl_b64 s[6:7], s[4:5], 2
	v_lshl_or_b32 v0, v2, 4, s8
	v_mov_b32_e32 v1, s9
	s_lshl_b64 s[8:9], s[4:5], 12
	v_lshl_or_b32 v2, v2, 3, s10
	v_mov_b32_e32 v3, s11
	s_lshl_b64 s[10:11], s[4:5], 11
	s_barrier
	s_branch .LBB0_788

.LBB0_845:
	s_or_b64 exec, exec, s[4:5]
	s_waitcnt lgkmcnt(0)
	v_mov_b32_e32 v0, 0
	v_readlane_b32 s4, v255, 20
	v_mbcnt_lo_u32_b32 v0, -1, v0
	v_mbcnt_hi_u32_b32 v0, -1, v0
	v_add_u32_e32 v10, s33, v0
	v_readlane_b32 s5, v255, 21
	s_and_b64 vcc, exec, s[4:5]
	v_readfirstlane_b32 s3, v10
	s_cbranch_vccz .LBB0_848
	s_and_b32 s1, s66, 0x7fffffc0
	s_mov_b64 s[6:7], 0
	s_cmpk_lg_i32 s1, 0x400
	s_mov_b64 s[4:5], 0
	s_cbranch_scc1 .LBB0_849
	s_and_b32 s20, s66, 15
	s_bfe_u32 s18, s66, 0x20004
	s_mov_b32 s8, 64
	s_mov_b64 s[4:5], -1
	s_branch .LBB0_849

.LBB0_855:
	s_andn2_b64 vcc, exec, s[4:5]
	s_cbranch_vccz .Lmy_bsk7
	s_barrier
	s_branch .LBB0_940
.Lmy_bsk7:
	s_ashr_i32 s10, s3, 8
	s_lshl_b32 s2, s10, 6
	s_add_u32 s16, s82, 0x24200
	s_addc_u32 s17, s83, 0
	s_cmp_lg_u32 s8, 64
	s_cselect_b64 s[6:7], -1, 0
	s_cmp_eq_u32 s8, 64
	s_cselect_b64 s[4:5], -1, 0
	s_and_b64 vcc, s[4:5], exec
	s_cselect_b32 s1, 4, 16
	s_lshl_b32 s9, s8, 8
	v_and_b32_e32 v11, 15, v10
	s_add_i32 s9, s9, s2
	v_or_b32_e32 v0, s9, v11
	v_ashrrev_i32_e32 v1, 31, v0
	v_lshl_add_u64 v[0:1], v[0:1], 2, s[16:17]
	s_barrier
	global_load_dword v244, v[0:1], off
	global_load_dword v243, v[0:1], off offset:64
	global_load_dword v242, v[0:1], off offset:128
	global_load_dword v241, v[0:1], off offset:192
	v_mov_b32_e32 v239, 1.0
	v_mov_b32_e32 v240, 1.0
	s_cbranch_vccnz .LBB0_860
	global_load_dword v240, v[0:1], off offset:512
	v_cndmask_b32_e64 v2, 0, 1, s[6:7]
	v_cmp_ne_u32_e64 s[12:13], 1, v2
	s_andn2_b64 vcc, exec, s[6:7]
	s_cbranch_vccz .LBB0_861

.LBB0_992:
	v_writelane_b32 v255, s66, 24
	s_nop 1
	v_writelane_b32 v255, s67, 25
	s_or_b64 exec, exec, s[4:5]
	s_waitcnt lgkmcnt(0)
	v_mov_b32_e32 v0, 0
	s_mov_b32 s4, 0
	v_mbcnt_lo_u32_b32 v0, -1, v0
	v_mbcnt_hi_u32_b32 v0, -1, v0
	v_add_u32_e32 v96, s33, v0
	s_ashr_i32 s5, s4, 31
	v_readfirstlane_b32 s1, v96
	s_ashr_i32 s3, s1, 6
	s_lshl_b64 s[4:5], s[4:5], 3
	v_readlane_b32 s6, v255, 2
	v_readlane_b32 s7, v255, 3
	s_add_u32 s4, s6, s4
	s_addc_u32 s5, s7, s5
	s_barrier
	s_load_dwordx2 s[4:5], s[4:5], 0x38
	v_mov_b32_e32 v67, 0
	v_and_b32_e32 v97, 63, v96
	v_lshlrev_b32_e32 v64, 3, v96
	s_waitcnt lgkmcnt(0)
	s_add_u32 s4, s4, 0x2000
	s_addc_u32 s5, s5, 0
	v_writelane_b32 v255, s4, 20
	s_nop 1
	v_writelane_b32 v255, s5, 21
	s_mov_b32 s4, 0
	s_ashr_i32 s5, s4, 31
	s_lshl_b64 s[4:5], s[4:5], 3
	s_add_u32 s4, s6, s4
	s_addc_u32 s5, s7, s5
	s_load_dwordx2 s[4:5], s[4:5], 0x40
	s_waitcnt lgkmcnt(0)
	s_add_u32 s4, s4, 0x80000
	s_addc_u32 s5, s5, 0
	v_writelane_b32 v255, s4, 52
	s_nop 1
	v_writelane_b32 v255, s5, 53
	s_mov_b32 s4, 0
	s_ashr_i32 s5, s4, 31
	s_lshl_b64 s[4:5], s[4:5], 3
	s_add_u32 s4, s6, s4
	s_addc_u32 s5, s7, s5
	s_load_dwordx2 s[6:7], s[4:5], 0x48
	s_mov_b32 s5, 0
	s_waitcnt lgkmcnt(0)
	s_add_u32 s8, s6, 0x1000
	s_addc_u32 s9, s7, 0
	v_readlane_b32 s6, v255, 43
	v_readlane_b32 s7, v255, 44
	s_and_b64 vcc, exec, s[6:7]
	s_cbranch_vccnz .LBB0_1061
	v_and_b32_e32 v0, 3, v96
	v_lshlrev_b32_e32 v5, 5, v0
	v_lshlrev_b32_e32 v66, 7, v0
	v_lshlrev_b32_e32 v9, 2, v0
	v_lshrrev_b32_e32 v0, 3, v96
	s_lshl_b32 s4, s3, 2
	v_and_b32_e32 v0, 2, v0
	v_bfe_u32 v2, v96, 1, 1
	v_bfe_u32 v3, v96, 2, 2
	v_readlane_b32 s6, v255, 52
	v_or3_b32 v0, s4, v0, v2
	s_movk_i32 s2, 0x80
	v_readlane_b32 s7, v255, 53
	v_lshlrev_b32_e32 v2, 6, v3
	v_lshlrev_b32_e32 v0, 4, v0
	v_cmp_gt_i32_e32 vcc, s2, v96
	s_add_i32 s2, 0, 0x18000
	v_lshl_add_u64 v[70:71], s[6:7], 0, v[66:67]
	v_xad_u32 v13, v0, v2, 0
	v_lshlrev_b32_e32 v0, 8, v96
	s_lshl_b32 s6, s3, 5
	v_lshl_add_u32 v98, v96, 2, s2
	v_ashrrev_i32_e32 v68, 2, v96
	v_add_u32_e32 v99, s2, v66
	s_add_i32 s2, 0, 0x10000
	v_and_b32_e32 v0, 0x1f00, v0
	s_ashr_i32 s7, s6, 31
	v_lshl_add_u32 v7, v68, 8, s2
	v_add_u32_e32 v16, s2, v0
	s_lshl_b64 s[10:11], s[6:7], 1
	v_readlane_b32 s2, v255, 31
	v_lshrrev_b32_e32 v1, 5, v97
	s_add_u32 s10, s2, s10
	v_readlane_b32 s2, v255, 33
	s_addc_u32 s11, s2, s11
	v_lshlrev_b32_e32 v66, 3, v1
	v_or_b32_e32 v19, 8, v5
	v_or_b32_e32 v20, 16, v5
	v_lshl_add_u64 v[72:73], s[10:11], 0, v[66:67]
	s_lshl_b64 s[6:7], s[6:7], 2
	v_readlane_b32 s10, v255, 20
	v_cmp_le_i32_e64 s[28:29], v19, v68
	v_or_b32_e32 v19, 9, v5
	v_cmp_le_i32_e64 s[46:47], v20, v68
	v_or_b32_e32 v20, 17, v5
	v_or_b32_e32 v21, 24, v5
	v_readlane_b32 s11, v255, 21
	s_add_u32 s6, s10, s6
	v_or_b32_e32 v18, 2, v5
	v_cmp_le_i32_e64 s[30:31], v19, v68
	v_or_b32_e32 v19, 10, v5
	v_cmp_le_i32_e64 s[48:49], v20, v68
	v_or_b32_e32 v20, 18, v5
	v_cmp_le_i32_e64 s[62:63], v21, v68
	v_or_b32_e32 v21, 25, v5
	s_addc_u32 s7, s11, s7
	s_add_i32 s10, s3, 40
	v_cmp_le_i32_e64 s[16:17], v18, v68
	v_or_b32_e32 v18, 3, v5
	v_cmp_le_i32_e64 s[34:35], v19, v68
	v_or_b32_e32 v19, 11, v5
	v_cmp_le_i32_e64 s[50:51], v20, v68
	v_or_b32_e32 v20, 19, v5
	v_cmp_le_i32_e64 s[64:65], v21, v68
	v_or_b32_e32 v21, 26, v5
	v_lshlrev_b32_e32 v66, 4, v1
	v_lshl_or_b32 v10, s10, 6, v97
	s_lshl_b32 s78, s10, 10
	s_add_i32 s10, s3, 48
	v_cmp_le_i32_e64 s[18:19], v18, v68
	v_or_b32_e32 v18, 4, v5
	v_cmp_le_i32_e64 s[36:37], v19, v68
	v_or_b32_e32 v19, 12, v5
	v_cmp_le_i32_e64 s[52:53], v20, v68
	v_or_b32_e32 v20, 20, v5
	v_cmp_le_i32_e64 s[66:67], v21, v68
	v_or_b32_e32 v21, 27, v5
	v_lshl_add_u64 v[74:75], s[6:7], 0, v[66:67]
	s_andn2_b32 s1, s1, 63
	s_add_i32 s2, s3, 8
	s_add_i32 s4, s3, 16
	s_add_i32 s6, s3, 24
	s_add_i32 s7, s3, 32
	v_lshl_or_b32 v12, s10, 6, v97
	s_lshl_b32 s79, s10, 10
	s_add_i32 s10, s3, 56
	v_cmp_le_i32_e64 s[20:21], v18, v68
	v_or_b32_e32 v18, 5, v5
	v_cmp_le_i32_e64 s[38:39], v19, v68
	v_or_b32_e32 v19, 13, v5
	v_cmp_le_i32_e64 s[54:55], v20, v68
	v_or_b32_e32 v20, 21, v5
	v_cmp_le_i32_e64 s[68:69], v21, v68
	v_or_b32_e32 v21, 28, v5
	v_or_b32_e32 v0, s1, v97
	v_lshl_or_b32 v2, s2, 6, v97
	v_lshl_or_b32 v4, s4, 6, v97
	v_lshl_or_b32 v6, s6, 6, v97
	v_lshl_or_b32 v8, s7, 6, v97
	v_lshl_or_b32 v14, s10, 6, v97
	v_cmp_le_i32_e64 s[22:23], v18, v68
	v_or_b32_e32 v18, 6, v5
	v_cmp_le_i32_e64 s[40:41], v19, v68
	v_or_b32_e32 v19, 14, v5
	v_cmp_le_i32_e64 s[56:57], v20, v68
	v_or_b32_e32 v20, 22, v5
	v_cmp_le_i32_e64 s[70:71], v21, v68
	v_or_b32_e32 v21, 29, v5
	v_and_b32_e32 v11, 15, v68
	v_ashrrev_i32_e32 v100, 5, v0
	v_ashrrev_i32_e32 v101, 5, v2
	v_ashrrev_i32_e32 v102, 5, v4
	v_ashrrev_i32_e32 v103, 5, v6
	v_ashrrev_i32_e32 v104, 5, v8
	v_ashrrev_i32_e32 v105, 5, v10
	v_ashrrev_i32_e32 v106, 5, v12
	v_ashrrev_i32_e32 v107, 5, v14
	v_cmp_le_i32_e64 s[12:13], v5, v68
	v_cmp_lt_i32_e64 s[14:15], v5, v68
	v_cmp_le_i32_e64 s[24:25], v18, v68
	v_or_b32_e32 v18, 7, v5
	v_cmp_le_i32_e64 s[42:43], v19, v68
	v_or_b32_e32 v19, 15, v5
	v_cmp_le_i32_e64 s[58:59], v20, v68
	v_or_b32_e32 v20, 23, v5
	v_cmp_le_i32_e64 s[72:73], v21, v68
	v_or_b32_e32 v21, 30, v5
	v_or_b32_e32 v5, 31, v5
	v_and_b32_e32 v65, 31, v96
	v_and_b32_e32 v15, 8, v64
	v_and_b32_e32 v17, 15, v96
	v_lshlrev_b32_e32 v0, 2, v100
	v_lshlrev_b32_e32 v2, 2, v101
	v_lshlrev_b32_e32 v4, 2, v102
	v_lshlrev_b32_e32 v6, 2, v103
	v_lshlrev_b32_e32 v8, 2, v104
	v_lshlrev_b32_e32 v10, 2, v105
	v_lshlrev_b32_e32 v12, 2, v106
	v_lshlrev_b32_e32 v14, 2, v107
	v_cmp_le_i32_e64 s[26:27], v18, v68
	v_bitop3_b32 v18, v9, v68, 15 bitop3:0x78
	v_cmp_le_i32_e64 s[44:45], v19, v68
	v_bitop3_b32 v19, v9, v11, 1 bitop3:0x36
	v_cmp_le_i32_e64 s[60:61], v20, v68
	v_bitop3_b32 v20, v9, v11, 2 bitop3:0x36
	v_cmp_le_i32_e64 s[76:77], v5, v68
	v_bitop3_b32 v5, v9, v11, 3 bitop3:0x36
	v_lshlrev_b32_e32 v9, 12, v1
	v_bitop3_b32 v0, v0, v65, 12 bitop3:0x6c
	v_bitop3_b32 v2, v2, v65, 12 bitop3:0x6c
	v_bitop3_b32 v4, v4, v65, 12 bitop3:0x6c
	v_bitop3_b32 v6, v6, v65, 12 bitop3:0x6c
	v_bitop3_b32 v8, v8, v65, 12 bitop3:0x6c
	v_bitop3_b32 v10, v10, v65, 12 bitop3:0x6c
	v_bitop3_b32 v12, v12, v65, 12 bitop3:0x6c
	v_bitop3_b32 v14, v14, v65, 12 bitop3:0x6c
	s_lshl_b32 s84, s10, 10
	v_cmp_le_i32_e64 s[74:75], v21, v68
	v_add3_u32 v9, v13, v15, v9
	v_bitop3_b32 v11, v1, v96, 15 bitop3:0x78
	v_bitop3_b32 v13, v1, v17, 2 bitop3:0x36
	v_bitop3_b32 v15, v1, v17, 4 bitop3:0x36
	v_bitop3_b32 v21, v1, v17, 6 bitop3:0x36
	v_bitop3_b32 v22, v1, v17, 8 bitop3:0x36
	v_bitop3_b32 v23, v1, v17, 10 bitop3:0x36
	v_bitop3_b32 v24, v1, v17, 12 bitop3:0x36
	v_bitop3_b32 v1, v1, v17, 14 bitop3:0x36
	v_readlane_b32 s10, v255, 24
	v_lshlrev_b32_e32 v0, 3, v0
	s_lshl_b32 s1, s3, 10
	v_lshlrev_b32_e32 v2, 3, v2
	s_lshl_b32 s2, s2, 10
	v_lshlrev_b32_e32 v4, 3, v4
	s_lshl_b32 s4, s4, 10
	v_lshlrev_b32_e32 v6, 3, v6
	s_lshl_b32 s6, s6, 10
	v_lshlrev_b32_e32 v8, 3, v8
	s_lshl_b32 s7, s7, 10
	v_lshlrev_b32_e32 v10, 3, v10
	v_lshlrev_b32_e32 v12, 3, v12
	v_lshlrev_b32_e32 v14, 3, v14
	v_lshlrev_b32_e32 v18, 4, v18
	v_lshlrev_b32_e32 v19, 4, v19
	v_lshlrev_b32_e32 v20, 4, v20
	v_lshlrev_b32_e32 v5, 4, v5
	v_lshlrev_b32_e32 v3, 9, v3
	v_lshlrev_b32_e32 v11, 4, v11
	v_lshlrev_b32_e32 v13, 4, v13
	v_lshlrev_b32_e32 v15, 4, v15
	v_lshlrev_b32_e32 v21, 4, v21
	v_lshlrev_b32_e32 v22, 4, v22
	v_lshlrev_b32_e32 v23, 4, v23
	v_lshlrev_b32_e32 v24, 4, v24
	v_lshlrev_b32_e32 v1, 4, v1
	v_readlane_b32 s11, v255, 25
	s_mov_b32 s88, s10
	v_ashrrev_i32_e32 v69, 31, v68
	v_or_b32_e32 v108, 32, v65
	v_or_b32_e32 v109, 64, v65
	v_or_b32_e32 v110, 0x60, v65
	s_lshl_b32 s85, s10, 4
	s_lshl_b32 s94, s0, 4
	v_lshlrev_b32_e32 v76, 1, v0
	s_add_i32 s95, s1, 0
	v_lshlrev_b32_e32 v66, 1, v2
	s_add_i32 s10, s2, 0
	v_lshlrev_b32_e32 v78, 1, v4
	s_add_i32 s11, s4, 0
	v_lshlrev_b32_e32 v80, 1, v6
	s_add_i32 s86, s6, 0
	v_lshlrev_b32_e32 v82, 1, v8
	s_add_i32 s87, s7, 0
	v_lshlrev_b32_e32 v84, 1, v10
	s_add_i32 s6, s78, 0
	v_lshlrev_b32_e32 v86, 1, v12
	s_add_i32 s7, s79, 0
	v_lshlrev_b32_e32 v88, 1, v14
	s_add_i32 s92, s84, 0
	v_mov_b32_e32 v111, 0x358637bd
	v_add_u32_e32 v112, v7, v18
	v_add_u32_e32 v113, v7, v19
	v_add_u32_e32 v114, v7, v20
	v_add_u32_e32 v115, v7, v5
	v_add_u32_e32 v116, v9, v3
	v_add_u32_e32 v117, v16, v11
	v_add_u32_e32 v118, v16, v13
	v_add_u32_e32 v119, v16, v15
	v_add_u32_e32 v120, v16, v21
	v_add_u32_e32 v121, v16, v22
	v_add_u32_e32 v122, v16, v23
	v_add_u32_e32 v123, v16, v24
	v_add_u32_e32 v124, v16, v1
	v_mov_b32_e32 v77, v67
	s_mov_b32 s93, s88
	s_branch .LBB0_995

.LBB0_1118:
	s_or_b64 exec, exec, s[4:5]
	s_waitcnt lgkmcnt(0)
	v_mov_b32_e32 v0, 0
	v_readlane_b32 s4, v255, 16
	v_mbcnt_lo_u32_b32 v0, -1, v0
	v_mbcnt_hi_u32_b32 v0, -1, v0
	v_add_u32_e32 v1, s33, v0
	v_readlane_b32 s5, v255, 17
	s_and_b64 vcc, exec, s[4:5]
	v_readfirstlane_b32 s3, v1
	s_cbranch_vccz .LBB0_1121
	s_and_b32 s1, s84, 0x7fffffe0
	s_mov_b64 s[12:13], 0
	s_cmpk_lg_i32 s1, 0x100
	s_mov_b64 s[10:11], 0
	s_cbranch_scc1 .LBB0_1122
	s_and_b32 s6, s84, 3
	s_bfe_u32 s4, s84, 0x30002
	s_mov_b32 s8, 64
	s_mov_b64 s[10:11], -1
	s_branch .LBB0_1122

.LBB0_1128:
	s_andn2_b64 vcc, exec, s[10:11]
	s_cbranch_vccz .Lmy_bsk8
	s_barrier
	s_branch .LBB0_1181
.Lmy_bsk8:
	v_ashrrev_i32_e32 v2, 31, v1
	v_lshrrev_b32_e32 v2, 26, v2
	v_add_u32_e32 v2, v1, v2
	v_ashrrev_i32_e32 v10, 6, v2
	v_bfe_i32 v2, v1, 27, 1
	v_lshlrev_b32_e32 v0, 4, v1
	v_lshrrev_b32_e32 v2, 22, v2
	v_add_u32_e32 v2, v0, v2
	v_and_b32_e32 v2, 0xfffffc00, v2
	v_sub_u32_e32 v2, v0, v2
	v_lshrrev_b32_e32 v3, 4, v2
	v_bitop3_b32 v3, v3, v2, 32 bitop3:0x6c
	v_ashrrev_i32_e32 v2, 31, v2
	v_lshrrev_b32_e32 v2, 26, v2
	v_add_u32_e32 v2, v3, v2
	v_ashrrev_i32_e32 v11, 6, v2
	v_lshlrev_b32_e32 v4, 3, v10
	v_mul_i32_i24_e32 v5, 64, v11
	v_and_b32_e32 v4, -16, v4
	v_sub_u32_e32 v3, v3, v5
	v_mov_b32_e32 v5, 1
	v_add_u32_e32 v2, v11, v4
	v_lshlrev_b32_e32 v4, 5, v10
	v_ashrrev_i16_sdwa v3, v5, sext(v3) dst_sel:DWORD dst_unused:UNUSED_PAD src0_sel:DWORD src1_sel:BYTE_0
	v_and_b32_e32 v4, 32, v4
	v_bfe_i32 v12, v3, 0, 16
	v_and_b32_e32 v7, 3, v11
	s_mov_b32 s1, 0xfffe0
	v_add_lshl_u32 v4, v4, v12, 1
	v_add_u32_e32 v0, 0x2000, v0
	v_lshlrev_b32_e32 v3, 1, v2
	v_lshrrev_b32_e32 v6, 2, v2
	v_and_or_b32 v7, v2, s1, v7
	v_lshl_add_u32 v196, v2, 12, v4
	v_ashrrev_i32_e32 v2, 31, v0
	v_lshrrev_b32_e32 v2, 22, v2
	v_add_u32_e32 v2, v0, v2
	v_ashrrev_i32_e32 v13, 10, v2
	v_mul_i32_i24_e32 v2, 0x400, v13
	v_sub_u32_e32 v0, v0, v2
	v_and_b32_e32 v3, 24, v3
	v_and_b32_e32 v6, 4, v6
	v_lshrrev_b32_e32 v2, 4, v0
	v_or3_b32 v3, v7, v6, v3
	v_bitop3_b32 v0, v2, v0, 32 bitop3:0x6c
	s_add_u32 s38, s82, 0x1567300
	v_lshl_add_u32 v198, v3, 12, v4
	v_ashrrev_i32_e32 v3, 31, v0
	s_addc_u32 s39, s83, 0
	s_ashr_i32 s2, s3, 6
	v_lshrrev_b32_e32 v3, 26, v3
	v_add_u32_e32 v3, v0, v3
	s_ashr_i32 s10, s3, 8
	s_lshl_b32 s40, s2, 10
	v_lshlrev_b32_e32 v2, 3, v13
	v_ashrrev_i32_e32 v14, 6, v3
	v_and_b32_e32 v3, 0xc0, v3
	s_cmp_eq_u32 s8, 64
	v_and_b32_e32 v2, -16, v2
	v_sub_u32_e32 v0, v0, v3
	s_cselect_b64 s[12:13], -1, 0
	v_add_u32_e32 v2, v14, v2
	v_ashrrev_i16_sdwa v0, v5, sext(v0) dst_sel:DWORD dst_unused:UNUSED_PAD src0_sel:DWORD src1_sel:BYTE_0
	v_and_b32_e32 v5, 3, v14
	s_and_b64 s[14:15], s[12:13], exec
	v_and_or_b32 v5, v2, s1, v5
	s_cselect_b32 s1, 4, 32
	s_ashr_i32 s5, s4, 31
	s_ashr_i32 s7, s6, 31
	s_ashr_i32 s9, s8, 31
	s_lshl_b64 s[14:15], s[4:5], 9
	s_lshl_b64 s[16:17], s[6:7], 20
	s_add_u32 s5, s38, s16
	s_addc_u32 s7, s39, s17
	s_add_u32 s34, s5, s14
	s_addc_u32 s35, s7, s15
	s_add_i32 s7, s40, 0
	s_add_i32 m0, s7, 0x10000
	s_lshl_b64 s[16:17], s[8:9], 20
	s_barrier
	global_load_lds_dwordx4 v198, s[34:35]
	s_add_i32 m0, s7, 0x12000
	v_lshlrev_b32_e32 v4, 5, v13
	v_bfe_i32 v15, v0, 0, 16
	v_lshlrev_b32_e32 v0, 1, v2
	v_lshrrev_b32_e32 v3, 2, v2
	s_add_u32 s5, s60, s16
	v_and_b32_e32 v4, 32, v4
	v_and_b32_e32 v0, 24, v0
	v_and_b32_e32 v3, 4, v3
	s_addc_u32 s9, s61, s17
	v_or3_b32 v0, v5, v3, v0
	v_add_lshl_u32 v3, v4, v15, 1
	s_add_u32 s30, s5, s14
	v_lshl_add_u32 v202, v0, 12, v3
	s_addc_u32 s31, s9, s15
	s_add_i32 s41, s7, 0x2000
	global_load_lds_dwordx4 v202, s[34:35]
	s_mov_b32 m0, s7
	s_add_u32 s14, s34, 0x80000
	v_lshl_add_u32 v200, v2, 12, v3
	global_load_lds_dwordx4 v196, s[30:31]
	s_mov_b32 m0, s41
	s_addc_u32 s15, s35, 0
	s_add_i32 s42, s7, 0x14000
	global_load_lds_dwordx4 v200, s[30:31]
	s_mov_b32 m0, s42
	s_add_i32 s43, s7, 0x16000
	global_load_lds_dwordx4 v198, s[14:15]
	s_mov_b32 m0, s43
	v_mov_b32_e32 v0, 0
	global_load_lds_dwordx4 v202, s[14:15]
	s_add_u32 s14, s30, 0x80000
	s_addc_u32 s15, s31, 0
	s_add_i32 s44, s7, 0x4000
	s_mov_b32 m0, s44
	s_add_i32 s45, s7, 0x6000
	global_load_lds_dwordx4 v196, s[14:15]
	s_mov_b32 m0, s45
	v_mov_b32_e32 v199, v0
	global_load_lds_dwordx4 v200, s[14:15]
	v_mov_b32_e32 v203, v0
	v_mov_b32_e32 v197, v0
	v_mov_b32_e32 v201, v0
	s_mov_b32 s9, 0
	v_lshl_add_u64 v[8:9], s[34:35], 0, v[198:199]
	v_lshl_add_u64 v[6:7], s[34:35], 0, v[202:203]
	v_lshl_add_u64 v[4:5], s[30:31], 0, v[196:197]
	s_cmp_lg_u32 s10, 1
	v_lshl_add_u64 v[2:3], s[30:31], 0, v[200:201]
	s_cbranch_scc1 .LBB0_1131
	s_barrier

.Lmy_bsk9:
	v_readlane_b32 s6, v255, 13
	s_lshl_b32 s4, s0, 3
	s_ashr_i32 s3, s2, 31
	s_ashr_i32 s5, s6, 31
	s_add_u32 s8, s2, s6
	s_addc_u32 s9, s3, s5
	s_lshl_b64 s[2:3], s[8:9], 2
	s_add_u32 s2, s2, 0x44600
	s_addc_u32 s3, s3, 0
	s_add_i32 s12, s1, 0x4000
	v_and_b32_e32 v2, 63, v20
	s_ashr_i32 s13, s12, 31
	v_lshlrev_b32_e32 v0, 2, v2
	s_ashr_i32 s5, s4, 31
	s_lshl_b64 s[8:9], s[8:9], 12
	s_lshl_b64 s[12:13], s[12:13], 11
	v_cmp_eq_u32_e64 s[10:11], 0, v2
	v_xor_b32_e32 v22, 0x80, v0
	v_xor_b32_e32 v23, 64, v0
	v_xor_b32_e32 v24, 32, v0
	v_xor_b32_e32 v25, 16, v0
	v_xor_b32_e32 v26, 8, v0
	v_xor_b32_e32 v27, 4, v0
	s_lshl_b64 s[6:7], s[4:5], 2
	v_lshl_or_b32 v0, v2, 4, s8
	v_mov_b32_e32 v1, s9
	s_lshl_b64 s[8:9], s[4:5], 12
	v_lshl_or_b32 v2, v2, 3, s12
	v_mov_b32_e32 v3, s13
	s_lshl_b64 s[12:13], s[4:5], 11
	s_barrier
	s_branch .LBB0_1260

.LBB0_1317:
	s_or_b64 exec, exec, s[4:5]
	s_waitcnt lgkmcnt(0)
	v_mov_b32_e32 v0, 0
	v_readlane_b32 s2, v255, 41
	v_mbcnt_lo_u32_b32 v0, -1, v0
	v_mbcnt_hi_u32_b32 v0, -1, v0
	v_add_u32_e32 v10, s33, v0
	v_readlane_b32 s3, v255, 42
	s_and_b64 vcc, exec, s[2:3]
	v_readfirstlane_b32 s3, v10
	s_cbranch_vccnz .LBB0_1323
	s_ashr_i32 s1, s84, 31
	s_lshr_b32 s1, s1, 29
	s_add_i32 s1, s84, s1
	s_and_b32 s2, s1, -8
	s_sub_i32 s2, s84, s2
	s_cmp_gt_i32 s2, 5
	s_cbranch_scc0 .LBB0_1320
	s_mul_i32 s4, s2, 0xb2
	s_add_i32 s6, s4, 6
	s_cbranch_execz .LBB0_1321
	s_branch .LBB0_1322

.LBB0_1323:
	v_readlane_b32 s4, v255, 41
	v_readlane_b32 s5, v255, 42
	s_and_b64 vcc, exec, s[4:5]
	s_cbranch_vccz .Lmy_bsk10
	s_barrier
	s_branch .LBB0_1369
.Lmy_bsk10:
	s_ashr_i32 s8, s3, 8
	s_lshl_b32 s2, s8, 6
	s_add_u32 s4, s82, 0x34600
	s_addc_u32 s5, s83, 0
	s_cmp_eq_u32 s20, 64
	s_cselect_b64 s[12:13], -1, 0
	s_cmp_lg_u32 s20, 64
	s_cselect_b64 s[6:7], -1, 0
	s_lshl_b32 s9, s20, 8
	v_and_b32_e32 v11, 15, v10
	s_add_i32 s9, s9, s2
	v_or_b32_e32 v0, s9, v11
	v_ashrrev_i32_e32 v1, 31, v0
	s_mov_b32 s1, 16
	v_lshl_add_u64 v[0:1], v[0:1], 2, s[4:5]
	s_barrier
	global_load_dword v233, v[0:1], off
	global_load_dword v232, v[0:1], off offset:64
	global_load_dword v231, v[0:1], off offset:128
	global_load_dword v230, v[0:1], off offset:192
	v_mov_b32_e32 v228, 1.0
	s_and_b64 vcc, exec, s[12:13]
	v_mov_b32_e32 v229, 1.0
	s_cbranch_vccnz .LBB0_1328
	global_load_dword v229, v[0:1], off offset:512
	v_cndmask_b32_e64 v2, 0, 1, s[6:7]
	v_cmp_ne_u32_e64 s[10:11], 1, v2
	s_andn2_b64 vcc, exec, s[6:7]
	s_cbranch_vccz .LBB0_1329

.LBB0_1430:
	s_or_b64 exec, exec, s[4:5]
	s_waitcnt lgkmcnt(0)
	v_mov_b32_e32 v0, 0
	v_readlane_b32 s4, v255, 16
	v_mbcnt_lo_u32_b32 v0, -1, v0
	v_mbcnt_hi_u32_b32 v0, -1, v0
	v_add_u32_e32 v1, s33, v0
	v_readlane_b32 s5, v255, 17
	s_and_b64 vcc, exec, s[4:5]
	v_readfirstlane_b32 s3, v1
	s_cbranch_vccz .LBB0_1433
	s_mov_b64 s[8:9], 0
	s_cmpk_gt_u32 s84, 0x12b
	s_mov_b64 s[6:7], 0
	s_cbranch_scc1 .LBB0_1434
	s_bfe_u32 s4, s84, 0x40002
	s_and_b32 s35, s84, 3
	s_mov_b32 s1, 64
	s_mov_b64 s[6:7], -1
	s_branch .LBB0_1434

.Lmy_bsk11:
	v_ashrrev_i32_e32 v2, 31, v1
	v_lshrrev_b32_e32 v2, 26, v2
	v_add_u32_e32 v2, v1, v2
	v_ashrrev_i32_e32 v10, 6, v2
	v_bfe_i32 v2, v1, 27, 1
	v_lshlrev_b32_e32 v0, 4, v1
	v_lshrrev_b32_e32 v2, 22, v2
	v_add_u32_e32 v2, v0, v2
	v_and_b32_e32 v2, 0xfffffc00, v2
	v_sub_u32_e32 v2, v0, v2
	v_lshrrev_b32_e32 v3, 4, v2
	v_bitop3_b32 v3, v3, v2, 32 bitop3:0x6c
	v_ashrrev_i32_e32 v2, 31, v2
	v_lshrrev_b32_e32 v2, 26, v2
	v_lshlrev_b32_e32 v4, 3, v10
	v_add_u32_e32 v2, v3, v2
	v_and_b32_e32 v4, -16, v4
	v_ashrrev_i32_e32 v12, 6, v2
	v_add_u32_e32 v2, v12, v4
	v_lshlrev_b32_e32 v4, 5, v10
	v_and_b32_e32 v11, 32, v4
	v_mul_i32_i24_e32 v4, 64, v12
	v_sub_u32_e32 v3, v3, v4
	v_mov_b32_e32 v4, 1
	v_ashrrev_i16_sdwa v3, v4, sext(v3) dst_sel:DWORD dst_unused:UNUSED_PAD src0_sel:DWORD src1_sel:BYTE_0
	v_lshlrev_b32_e32 v5, 1, v2
	v_lshrrev_b32_e32 v6, 2, v2
	v_and_b32_e32 v7, 3, v12
	s_mov_b32 s2, 0xffffe0
	v_bfe_i32 v13, v3, 0, 16
	v_and_b32_e32 v5, 24, v5
	v_and_b32_e32 v6, 4, v6
	v_and_or_b32 v7, v2, s2, v7
	s_movk_i32 s6, 0xb00
	v_add_u32_e32 v3, v11, v13
	v_or3_b32 v5, v7, v6, v5
	v_mul_lo_u32 v2, v2, s6
	v_add_lshl_u32 v196, v3, v2, 1
	v_mul_u32_u24_e32 v2, 0xb00, v5
	v_add_u32_e32 v0, 0x2000, v0
	v_add_lshl_u32 v198, v2, v3, 1
	v_ashrrev_i32_e32 v2, 31, v0
	v_lshrrev_b32_e32 v2, 22, v2
	v_add_u32_e32 v2, v0, v2
	v_ashrrev_i32_e32 v14, 10, v2
	v_mul_i32_i24_e32 v2, 0x400, v14
	v_sub_u32_e32 v0, v0, v2
	v_lshrrev_b32_e32 v2, 4, v0
	s_add_u32 s10, s82, 0x4ae7300
	v_bitop3_b32 v0, v2, v0, 32 bitop3:0x6c
	s_addc_u32 s11, s83, 0
	s_ashr_i32 s8, s3, 6
	v_ashrrev_i32_e32 v3, 31, v0
	v_lshrrev_b32_e32 v3, 26, v3
	s_ashr_i32 s12, s3, 8
	s_lshl_b32 s34, s8, 10
	v_lshlrev_b32_e32 v2, 3, v14
	v_add_u32_e32 v3, v0, v3
	s_cmp_eq_u32 s1, 64
	v_and_b32_e32 v2, -16, v2
	v_ashrrev_i32_e32 v15, 6, v3
	v_lshlrev_b32_e32 v5, 5, v14
	s_cselect_b64 s[16:17], -1, 0
	v_add_u32_e32 v2, v15, v2
	v_and_b32_e32 v16, 32, v5
	v_and_b32_e32 v5, 3, v15
	s_and_b64 s[14:15], s[16:17], exec
	v_and_or_b32 v5, v2, s2, v5
	s_cselect_b32 s2, 4, 44
	s_ashr_i32 s5, s4, 31
	s_lshl_b64 s[14:15], s[4:5], 9
	s_mul_i32 s7, s35, 0x160000
	s_mul_hi_i32 s5, s35, 0x160000
	s_add_u32 s7, s10, s7
	s_addc_u32 s5, s11, s5
	s_add_u32 s28, s7, s14
	v_and_b32_e32 v3, 0xc0, v3
	s_addc_u32 s29, s5, s15
	s_add_i32 s36, s34, 0
	v_sub_u32_e32 v0, v0, v3
	s_add_i32 m0, s36, 0x10000
	v_ashrrev_i16_sdwa v0, v4, sext(v0) dst_sel:DWORD dst_unused:UNUSED_PAD src0_sel:DWORD src1_sel:BYTE_0
	v_lshlrev_b32_e32 v3, 1, v2
	v_lshrrev_b32_e32 v4, 2, v2
	s_barrier
	global_load_lds_dwordx4 v198, s[28:29]
	s_add_i32 m0, s36, 0x12000
	s_mul_i32 s7, s1, 0x160000
	v_readlane_b32 s18, v255, 18
	v_bfe_i32 v17, v0, 0, 16
	v_and_b32_e32 v3, 24, v3
	v_and_b32_e32 v4, 4, v4
	s_mul_hi_i32 s5, s1, 0x160000
	v_readlane_b32 s19, v255, 19
	s_add_u32 s7, s18, s7
	v_add_u32_e32 v0, v16, v17
	v_or3_b32 v3, v5, v4, v3
	v_mul_lo_u32 v2, v2, s6
	s_addc_u32 s5, s19, s5
	v_add_lshl_u32 v200, v0, v2, 1
	v_mul_u32_u24_e32 v2, 0xb00, v3
	s_add_u32 s24, s7, s14
	v_add_lshl_u32 v202, v2, v0, 1
	s_addc_u32 s25, s5, s15
	s_add_i32 s37, s36, 0x2000
	global_load_lds_dwordx4 v202, s[28:29]
	s_mov_b32 m0, s36
	s_add_u32 s14, s28, 0xb0000
	global_load_lds_dwordx4 v196, s[24:25]
	s_mov_b32 m0, s37
	s_addc_u32 s15, s29, 0
	s_add_i32 s38, s36, 0x14000
	global_load_lds_dwordx4 v200, s[24:25]
	s_mov_b32 m0, s38
	s_add_i32 s39, s36, 0x16000
	global_load_lds_dwordx4 v198, s[14:15]
	s_mov_b32 m0, s39
	v_mov_b32_e32 v0, 0
	global_load_lds_dwordx4 v202, s[14:15]
	s_add_u32 s14, s24, 0xb0000
	s_addc_u32 s15, s25, 0
	s_add_i32 s40, s36, 0x4000
	s_mov_b32 m0, s40
	s_add_i32 s41, s36, 0x6000
	global_load_lds_dwordx4 v196, s[14:15]
	s_mov_b32 m0, s41
	v_mov_b32_e32 v199, v0
	global_load_lds_dwordx4 v200, s[14:15]
	v_mov_b32_e32 v203, v0
	v_mov_b32_e32 v197, v0
	v_mov_b32_e32 v201, v0
	s_mov_b32 s7, 0
	v_lshl_add_u64 v[8:9], s[28:29], 0, v[198:199]
	v_lshl_add_u64 v[6:7], s[28:29], 0, v[202:203]
	v_lshl_add_u64 v[4:5], s[24:25], 0, v[196:197]
	s_cmp_lg_u32 s12, 1
	v_lshl_add_u64 v[2:3], s[24:25], 0, v[200:201]
	s_cbranch_scc1 .LBB0_1443
	s_barrier

.Lmy_bsk12:
	v_readlane_b32 s6, v255, 13
	s_lshl_b32 s4, s0, 3
	s_ashr_i32 s3, s2, 31
	s_ashr_i32 s5, s6, 31
	s_add_u32 s8, s2, s6
	s_addc_u32 s9, s3, s5
	s_lshl_b64 s[2:3], s[8:9], 2
	s_add_u32 s2, s2, 0x54a00
	s_addc_u32 s3, s3, 0
	s_add_i32 s10, s1, 0x4000
	v_and_b32_e32 v2, 63, v32
	s_ashr_i32 s11, s10, 31
	v_lshlrev_b32_e32 v0, 2, v2
	s_ashr_i32 s5, s4, 31
	s_lshl_b64 s[8:9], s[8:9], 12
	s_lshl_b64 s[10:11], s[10:11], 11
	v_cmp_eq_u32_e64 s[12:13], 0, v2
	v_xor_b32_e32 v34, 0x80, v0
	v_xor_b32_e32 v35, 64, v0
	v_xor_b32_e32 v36, 32, v0
	v_xor_b32_e32 v37, 16, v0
	v_xor_b32_e32 v38, 8, v0
	v_xor_b32_e32 v39, 4, v0
	s_lshl_b64 s[6:7], s[4:5], 2
	v_lshl_or_b32 v0, v2, 4, s8
	v_mov_b32_e32 v1, s9
	s_lshl_b64 s[8:9], s[4:5], 12
	v_lshl_or_b32 v2, v2, 3, s10
	v_mov_b32_e32 v3, s11
	s_lshl_b64 s[14:15], s[4:5], 11
	s_barrier
	s_branch .LBB0_1596

.LBB0_1653:
	s_or_b64 exec, exec, s[4:5]
	s_waitcnt lgkmcnt(0)
	v_mov_b32_e32 v0, 0
	s_cmpk_lt_i32 s84, 0xc3
	v_mbcnt_lo_u32_b32 v0, -1, v0
	v_mbcnt_hi_u32_b32 v0, -1, v0
	v_add_u32_e32 v10, s33, v0
	s_cselect_b64 s[6:7], -1, 0
	s_cmpk_gt_i32 s84, 0xc2
	v_readfirstlane_b32 s3, v10
	s_cbranch_scc1 .LBB0_1659
	s_ashr_i32 s1, s84, 31
	s_lshr_b32 s1, s1, 29
	s_add_i32 s1, s84, s1
	s_and_b32 s2, s1, -8
	s_sub_i32 s2, s84, s2
	s_cmp_gt_i32 s2, 2
	s_cbranch_scc0 .LBB0_1656
	s_mul_i32 s4, s2, 24
	s_or_b32 s8, s4, 3
	s_cbranch_execz .LBB0_1657
	s_branch .LBB0_1658

.LBB0_1659:
	s_add_u32 s90, s82, 0x264f7300
	s_addc_u32 s91, s83, 0
	s_add_u32 s78, s82, 0x1b647300
	s_addc_u32 s79, s83, 0
	s_andn2_b64 vcc, exec, s[6:7]
	s_cbranch_vccz .Lmy_bsk13
	s_barrier
	s_branch .LBB0_1880
.Lmy_bsk13:
	s_ashr_i32 s18, s3, 8
	s_lshl_b32 s2, s18, 6
	s_add_u32 s6, s82, 0x44a00
	s_addc_u32 s7, s83, 0
	s_cmp_eq_u32 s4, 64
	s_cselect_b64 s[16:17], -1, 0
	s_cmp_lg_u32 s4, 64
	s_cselect_b64 s[14:15], -1, 0
	s_lshl_b32 s5, s4, 8
	v_and_b32_e32 v11, 15, v10
	s_add_i32 s5, s5, s2
	v_or_b32_e32 v0, s5, v11
	v_ashrrev_i32_e32 v1, 31, v0
	s_mov_b32 s1, 16
	v_lshl_add_u64 v[0:1], v[0:1], 2, s[6:7]
	s_barrier
	global_load_dword v235, v[0:1], off
	global_load_dword v234, v[0:1], off offset:64
	global_load_dword v233, v[0:1], off offset:128
	global_load_dword v232, v[0:1], off offset:192
	v_mov_b32_e32 v230, 1.0
	s_and_b64 vcc, exec, s[16:17]
	v_mov_b32_e32 v231, 1.0
	s_cbranch_vccnz .LBB0_1664
	global_load_dword v231, v[0:1], off offset:512
	v_cndmask_b32_e64 v2, 0, 1, s[14:15]
	v_cmp_ne_u32_e64 s[12:13], 1, v2
	s_andn2_b64 vcc, exec, s[14:15]
	s_cbranch_vccz .LBB0_1665

.LBB0_1968:
	s_or_b64 exec, exec, s[4:5]
	s_waitcnt lgkmcnt(0)
	v_mov_b32_e32 v0, 0
	v_readlane_b32 s2, v255, 13
	v_mbcnt_lo_u32_b32 v0, -1, v0
	v_mbcnt_hi_u32_b32 v0, -1, v0
	v_add_u32_e32 v0, s33, v0
	s_mov_b32 s6, 0
	v_readfirstlane_b32 s1, v0
	s_ashr_i32 s1, s1, 6
	s_add_i32 s4, s1, s2
	v_mov_b32_e32 v1, 0
	s_cmpk_gt_i32 s4, 0x407f
	s_cbranch_scc0 .Lmy_bsk14
	s_barrier
	s_branch .LBB0_1973
.Lmy_bsk14:
	s_ashr_i32 s7, s6, 31
	s_lshl_b64 s[6:7], s[6:7], 3
	v_readlane_b32 s8, v255, 2
	v_readlane_b32 s9, v255, 3
	s_add_u32 s6, s8, s6
	s_addc_u32 s7, s9, s7
	s_barrier
	s_load_dwordx2 s[6:7], s[6:7], 0x80
	v_and_b32_e32 v2, 63, v0
	v_mov_b32_e32 v9, v1
	v_lshlrev_b32_e32 v8, 4, v2
	v_mov_b32_e32 v3, 0x500
	s_waitcnt lgkmcnt(0)
	v_lshl_add_u64 v[4:5], s[6:7], 0, v[8:9]
	v_lshlrev_b32_e32 v12, 3, v2
	v_mov_b32_e32 v13, v1
	v_mad_i64_i32 v[8:9], s[12:13], s4, v3, v[8:9]
	v_lshlrev_b32_e32 v0, 2, v2
	v_mad_i64_i32 v[6:7], s[8:9], s4, v3, v[12:13]
	s_mov_b64 s[12:13], 0x264f7300
	v_mov_b32_e32 v3, 0x280
	v_lshl_add_u64 v[8:9], v[8:9], 0, s[12:13]
	v_mad_i64_i32 v[10:11], s[12:13], s4, v3, v[0:1]
	s_mov_b64 s[12:13], 0x27947500
	s_nop 0
	v_lshl_add_u64 v[10:11], v[10:11], 0, s[12:13]
	v_mad_i64_i32 v[12:13], s[12:13], s4, v3, v[12:13]
	s_lshl_b32 s6, s0, 3
	s_lshl_b32 s2, s84, 8
	s_lshl_b32 s1, s1, 5
	s_ashr_i32 s5, s4, 31
	s_mov_b64 s[12:13], 0x27947300
	s_add_i32 s1, s2, s1
	s_lshl_b32 s2, s0, 8
	s_ashr_i32 s7, s6, 31
	v_lshl_add_u64 v[12:13], v[12:13], 0, s[12:13]
	s_lshl_b64 s[12:13], s[4:5], 7
	s_mov_b64 s[8:9], 0x264f7700
	s_add_u32 s11, s12, 0x34ff7300
	v_cmp_gt_u32_e32 vcc, 32, v2
	v_lshl_add_u64 v[6:7], v[6:7], 0, s[8:9]
	s_mul_i32 s8, s0, 0x2800
	s_mul_hi_i32 s9, s6, 0x500
	s_mul_i32 s14, s0, 0x1400
	s_mul_hi_i32 s15, s6, 0x280
	s_addc_u32 s22, s13, 0
	s_lshl_b64 s[16:17], s[6:7], 7
	v_mov_b32_e32 v3, 0x358637bd
	s_mov_b32 s23, 0x800000
	s_mov_b32 s24, 0x4080000
	v_lshlrev_b32_e32 v0, 2, v0
	s_mov_b32 s25, 0x5080000
	v_lshlrev_b32_e32 v14, 2, v2
	s_branch .LBB0_1971

.LBB0_2170:
	s_or_b64 exec, exec, s[4:5]
	s_waitcnt lgkmcnt(0)
	v_mov_b32_e32 v0, 0
	v_readlane_b32 s2, v255, 43
	v_mbcnt_lo_u32_b32 v0, -1, v0
	v_mbcnt_hi_u32_b32 v0, -1, v0
	v_add_u32_e32 v0, s33, v0
	v_readlane_b32 s3, v255, 44
	s_and_b64 vcc, exec, s[2:3]
	v_readfirstlane_b32 s1, v0
	s_cbranch_vccz .Lmy_bsk15
	s_barrier
	s_branch .LBB0_2202
.Lmy_bsk15:
	s_ashr_i32 s2, s84, 31
	s_lshr_b32 s3, s2, 29
	s_add_i32 s3, s84, s3
	s_and_b32 s4, s3, -8
	s_sub_i32 s7, s84, s4
	s_cmp_gt_i32 s7, -1
	s_cbranch_scc0 .LBB0_2173
	s_lshl_b32 s6, s7, 7
	s_cbranch_execz .LBB0_2174
	s_branch .LBB0_2175

.LBB0_2175:
	v_ashrrev_i32_e32 v2, 31, v0
	v_lshrrev_b32_e32 v2, 26, v2
	v_add_u32_e32 v2, v0, v2
	v_ashrrev_i32_e32 v10, 6, v2
	v_bfe_i32 v2, v0, 27, 1
	v_lshlrev_b32_e32 v1, 4, v0
	v_lshrrev_b32_e32 v2, 22, v2
	v_add_u32_e32 v2, v1, v2
	v_and_b32_e32 v2, 0xfffffc00, v2
	v_sub_u32_e32 v2, v1, v2
	v_lshrrev_b32_e32 v3, 4, v2
	v_bitop3_b32 v3, v3, v2, 32 bitop3:0x6c
	v_ashrrev_i32_e32 v2, 31, v2
	v_lshrrev_b32_e32 v2, 26, v2
	v_lshlrev_b32_e32 v4, 3, v10
	v_add_u32_e32 v2, v3, v2
	v_and_b32_e32 v4, -16, v4
	v_ashrrev_i32_e32 v12, 6, v2
	v_add_u32_e32 v2, v12, v4
	v_lshlrev_b32_e32 v4, 5, v10
	v_and_b32_e32 v11, 32, v4
	v_mul_i32_i24_e32 v4, 64, v12
	v_sub_u32_e32 v3, v3, v4
	v_mov_b32_e32 v4, 1
	v_ashrrev_i16_sdwa v3, v4, sext(v3) dst_sel:DWORD dst_unused:UNUSED_PAD src0_sel:DWORD src1_sel:BYTE_0
	v_bfe_i32 v13, v3, 0, 16
	v_lshlrev_b32_e32 v5, 1, v2
	v_lshrrev_b32_e32 v6, 2, v2
	v_and_b32_e32 v7, 3, v12
	s_mov_b32 s5, 0x7fffe0
	s_movk_i32 s8, 0x140
	v_add_u32_e32 v3, v11, v13
	v_and_b32_e32 v5, 24, v5
	v_and_b32_e32 v6, 4, v6
	v_and_or_b32 v7, v2, s5, v7
	v_mul_lo_u32 v2, v2, s8
	v_or3_b32 v5, v7, v6, v5
	v_add_lshl_u32 v196, v3, v2, 1
	v_lshlrev_b32_e32 v2, 1, v3
	v_add_u32_e32 v1, 0x2000, v1
	v_lshl_add_u32 v198, v5, 9, v2
	v_ashrrev_i32_e32 v2, 31, v1
	v_lshrrev_b32_e32 v2, 22, v2
	v_add_u32_e32 v2, v1, v2
	v_ashrrev_i32_e32 v14, 10, v2
	v_mul_i32_i24_e32 v2, 0x400, v14
	v_sub_u32_e32 v1, v1, v2
	v_lshrrev_b32_e32 v2, 4, v1
	s_ashr_i32 s4, s3, 3
	v_bitop3_b32 v1, v2, v1, 32 bitop3:0x6c
	s_add_u32 s3, s82, 0x6be7f300
	v_ashrrev_i32_e32 v3, 31, v1
	s_addc_u32 s10, s83, 0
	v_lshrrev_b32_e32 v3, 26, v3
	s_ashr_i32 s12, s1, 6
	s_ashr_i32 s9, s1, 8
	v_lshlrev_b32_e32 v2, 3, v14
	v_add_u32_e32 v3, v1, v3
	s_lshl_b32 s11, s12, 10
	v_and_b32_e32 v2, -16, v2
	v_ashrrev_i32_e32 v15, 6, v3
	v_lshlrev_b32_e32 v5, 5, v14
	s_add_u32 s34, s82, 0x27947300
	v_add_u32_e32 v2, v15, v2
	v_and_b32_e32 v16, 32, v5
	v_and_b32_e32 v5, 3, v15
	s_addc_u32 s35, s83, 0
	s_add_i32 s4, s6, s4
	v_and_or_b32 v5, v2, s5, v5
	s_ashr_i32 s5, s4, 31
	s_lshr_b32 s5, s5, 25
	s_add_i32 s5, s4, s5
	s_ashr_i32 s6, s5, 7
	s_and_b32 s5, s5, 0xffffff80
	s_sub_i32 s5, s4, s5
	s_bfe_i32 s4, s5, 0x80000
	s_bfe_u32 s4, s4, 0x3000c
	s_add_i32 s7, s5, s4
	s_bfe_i32 s4, s7, 0x80000
	s_and_b32 s7, s7, 0xf8
	s_sub_i32 s5, s5, s7
	s_lshl_b32 s6, s6, 3
	s_sext_i32_i8 s5, s5
	s_sext_i32_i16 s4, s4
	s_add_i32 s54, s6, s5
	s_lshr_b32 s4, s4, 3
	s_mul_hi_i32 s5, s54, 0x28000
	s_bfe_i64 s[6:7], s[4:5], 0x100000
	v_and_b32_e32 v3, 0xc0, v3
	s_lshl_b64 s[6:7], s[6:7], 17
	v_sub_u32_e32 v1, v1, v3
	s_add_u32 s28, s3, s6
	v_ashrrev_i16_sdwa v1, v4, sext(v1) dst_sel:DWORD dst_unused:UNUSED_PAD src0_sel:DWORD src1_sel:BYTE_0
	s_addc_u32 s29, s10, s7
	s_add_i32 s36, s11, 0
	s_mov_b32 s55, 4
	v_bfe_i32 v17, v1, 0, 16
	v_lshlrev_b32_e32 v3, 1, v2
	v_lshrrev_b32_e32 v4, 2, v2
	s_add_i32 m0, s36, 0x10000
	v_add_u32_e32 v1, v16, v17
	v_and_b32_e32 v3, 24, v3
	v_and_b32_e32 v4, 4, v4
	v_mul_lo_u32 v2, v2, s8
	s_mul_i32 s13, s54, 0x28000
	s_barrier
	global_load_lds_dwordx4 v198, s[28:29]
	s_add_i32 m0, s36, 0x12000
	v_or3_b32 v3, v5, v4, v3
	v_add_lshl_u32 v200, v1, v2, 1
	v_lshlrev_b32_e32 v1, 1, v1
	s_add_u32 s24, s34, s13
	v_lshl_add_u32 v202, v3, 9, v1
	s_addc_u32 s25, s35, s5
	s_add_i32 s37, s36, 0x2000
	global_load_lds_dwordx4 v202, s[28:29]
	s_mov_b32 m0, s36
	s_add_u32 s6, s28, 0x10000
	global_load_lds_dwordx4 v196, s[24:25]
	s_mov_b32 m0, s37
	s_addc_u32 s7, s29, 0
	s_add_i32 s38, s36, 0x14000
	global_load_lds_dwordx4 v200, s[24:25]
	s_mov_b32 m0, s38
	s_add_i32 s39, s36, 0x16000
	global_load_lds_dwordx4 v198, s[6:7]
	s_mov_b32 m0, s39
	v_mov_b32_e32 v1, 0
	global_load_lds_dwordx4 v202, s[6:7]
	s_add_u32 s6, s24, 0x14000
	s_addc_u32 s7, s25, 0
	s_add_i32 s40, s36, 0x4000
	s_mov_b32 m0, s40
	s_add_i32 s41, s36, 0x6000
	global_load_lds_dwordx4 v196, s[6:7]
	s_mov_b32 m0, s41
	v_mov_b32_e32 v199, v1
	global_load_lds_dwordx4 v200, s[6:7]
	v_mov_b32_e32 v203, v1
	v_mov_b32_e32 v197, v1
	v_mov_b32_e32 v201, v1
	s_mov_b32 s5, 0
	v_lshl_add_u64 v[8:9], s[28:29], 0, v[198:199]
	v_lshl_add_u64 v[6:7], s[28:29], 0, v[202:203]
	v_lshl_add_u64 v[4:5], s[24:25], 0, v[196:197]
	s_cmp_lg_u32 s9, 1
	v_lshl_add_u64 v[2:3], s[24:25], 0, v[200:201]
	s_cbranch_scc1 .LBB0_2177
	s_barrier

.LBB0_2254:
	s_or_b64 exec, exec, s[4:5]
	s_cmpk_lg_i32 s0, 0x100
	s_cselect_b64 s[2:3], -1, 0
	v_writelane_b32 v255, s2, 50
	s_mov_b64 s[4:5], -1
	s_and_b64 vcc, exec, s[2:3]
	v_writelane_b32 v255, s3, 51
	v_writelane_b32 v255, s86, 37
	s_waitcnt lgkmcnt(0)
	v_writelane_b32 v255, s87, 38
	v_writelane_b32 v255, s90, 35
	s_nop 1
	v_writelane_b32 v255, s91, 36
	v_writelane_b32 v255, s78, 47
	s_nop 1
	v_writelane_b32 v255, s79, 48
	s_cbranch_vccnz .Lmy_bsk17
	s_barrier
	s_branch .LBB0_2442
.Lmy_bsk17:
	s_and_b32 s1, s84, 0x7f
	s_mul_i32 s2, s1, 0x56
	s_lshr_b32 s2, s2, 8
	s_mul_i32 s2, s2, 3
	s_sub_i32 s1, s1, s2
	s_and_b32 s40, s1, 0xff
	s_add_u32 s1, s82, 0x3056f300
	v_writelane_b32 v255, s1, 43
	s_addc_u32 s1, s83, 0
	s_add_u32 s11, s82, 0x2836f300
	s_addc_u32 s52, s83, 0
	s_add_u32 s6, s82, 0x3466f300
	s_addc_u32 s7, s83, 0
	s_add_u32 s56, s82, 0x34a6f300
	s_addc_u32 s57, s83, 0
	v_writelane_b32 v255, s1, 26
	s_add_u32 s1, s82, 0x3600
	s_addc_u32 s54, s83, 0
	s_add_u32 s55, s80, 0x5480000
	s_addc_u32 s74, s81, 0
	s_add_u32 s58, s82, 0x26277300
	s_addc_u32 s59, s83, 0
	s_add_u32 s75, s82, 0x359ff300
	s_addc_u32 s76, s83, 0
	s_ashr_i32 s85, s84, 31
	v_writelane_b32 v255, s1, 31
	s_lshl_b64 s[2:3], s[84:85], 3
	v_writelane_b32 v255, s2, 33
	s_ashr_i32 s1, s0, 31
	s_lshl_b64 s[62:63], s[0:1], 3
	v_writelane_b32 v255, s3, 34
	s_add_i32 s3, 0, 0x10000
	s_mov_b32 s2, s84
	v_writelane_b32 v255, s2, 24
	s_mov_b32 s77, 0
	s_movk_i32 s78, 0x180
	v_writelane_b32 v255, s3, 25
	v_mov_b32_e32 v1, 0
	s_mov_b32 s79, 0x2aaaaaab
	s_movk_i32 s85, 0xffe8
	s_movk_i32 s94, 0x280
	s_movk_i32 s95, 0x1800
	s_movk_i32 s96, 0x1000
	s_mov_b64 s[64:65], 0x2000
	s_add_i32 s97, 0, 0x20800
	v_mov_b32_e32 v158, 0xa000
	v_mov_b32_e32 v159, 0x4000
	v_mov_b32_e32 v160, 0xf149f2ca
	v_mov_b32_e32 v161, 0x1f0
	v_mov_b32_e32 v162, 0x100
	s_mov_b32 s60, s84
	v_writelane_b32 v255, s40, 28
	s_cmp_lg_u32 s77, s40
	s_mov_b64 s[4:5], -1
	s_cbranch_scc0 .Lmy_bsk16
	s_barrier
	s_branch .LBB0_2342
.Lmy_bsk16:
	s_barrier
.LBB0_2256:
	s_andn2_b64 vcc, exec, s[4:5]
	s_cbranch_vccnz .LBB0_2391

.LBB0_2625:
	s_or_b64 exec, exec, s[4:5]
	s_add_u32 s88, s82, 0x6567300
	s_addc_u32 s1, s83, 0
	s_add_u32 s42, s82, 0x3056f300
	s_waitcnt lgkmcnt(0)
	v_mov_b32_e32 v0, 0
	s_addc_u32 s43, s83, 0
	s_cmp_lt_i32 s84, 8
	v_mbcnt_lo_u32_b32 v0, -1, v0
	v_writelane_b32 v255, s1, 35
	v_mbcnt_hi_u32_b32 v0, -1, v0
	s_cselect_b64 s[2:3], -1, 0
	v_add_u32_e32 v10, s33, v0
	v_writelane_b32 v255, s2, 28
	v_mov_b32_e32 v65, 0
	s_cmp_gt_i32 s84, 7
	v_readfirstlane_b32 s1, v10
	v_writelane_b32 v255, s3, 29
	s_mov_b32 s21, 8
	s_cbranch_scc0 .Lmy_bsk18
	s_barrier
	s_branch .LBB0_2636
.Lmy_bsk18:
	v_lshlrev_b32_e32 v0, 4, v10
	v_add_u32_e32 v1, 0x2000, v0
	v_ashrrev_i32_e32 v2, 31, v1
	v_lshrrev_b32_e32 v2, 22, v2
	v_add_u32_e32 v2, v1, v2
	v_ashrrev_i32_e32 v8, 10, v2
	v_mul_i32_i24_e32 v2, 0x400, v8
	v_sub_u32_e32 v1, v1, v2
	v_lshrrev_b32_e32 v2, 4, v1
	v_bitop3_b32 v1, v2, v1, 32 bitop3:0x6c
	v_ashrrev_i32_e32 v2, 31, v1
	v_lshrrev_b32_e32 v2, 26, v2
	v_add_u32_e32 v2, v1, v2
	v_lshlrev_b32_e32 v3, 3, v8
	v_ashrrev_i32_e32 v9, 6, v2
	v_and_b32_e32 v3, -16, v3
	v_add_u32_e32 v3, v9, v3
	v_and_b32_e32 v4, 3, v9
	s_mov_b32 s2, 0x3fffe0
	v_lshrrev_b32_e32 v5, 2, v3
	v_lshlrev_b32_e32 v6, 1, v3
	v_and_b32_e32 v2, 0xc0, v2
	v_and_or_b32 v4, v3, s2, v4
	v_and_b32_e32 v5, 4, v5
	v_and_b32_e32 v6, 24, v6
	v_sub_u32_e32 v1, v1, v2
	v_mov_b32_e32 v2, 1
	v_or3_b32 v4, v4, v5, v6
	v_lshlrev_b32_e32 v5, 5, v8
	v_ashrrev_i16_sdwa v1, v2, sext(v1) dst_sel:DWORD dst_unused:UNUSED_PAD src0_sel:DWORD src1_sel:BYTE_0
	v_and_b32_e32 v5, 32, v5
	v_bfe_i32 v11, v1, 0, 16
	v_add_lshl_u32 v1, v5, v11, 1
	v_lshl_add_u32 v66, v4, 10, v1
	v_lshl_add_u32 v68, v3, 13, v1
	v_bfe_i32 v1, v10, 27, 1
	v_lshrrev_b32_e32 v1, 22, v1
	v_add_u32_e32 v1, v0, v1
	v_and_b32_e32 v1, 0xfffffc00, v1
	v_sub_u32_e32 v0, v0, v1
	v_lshrrev_b32_e32 v1, 4, v0
	v_bitop3_b32 v1, v1, v0, 32 bitop3:0x6c
	v_ashrrev_i32_e32 v0, 31, v0
	v_lshrrev_b32_e32 v0, 26, v0
	v_add_u32_e32 v0, v1, v0
	v_ashrrev_i32_e32 v12, 6, v0
	v_ashrrev_i32_e32 v0, 31, v10
	v_lshrrev_b32_e32 v0, 26, v0
	v_add_u32_e32 v0, v10, v0
	v_ashrrev_i32_e32 v13, 6, v0
	v_lshlrev_b32_e32 v0, 3, v13
	v_and_b32_e32 v0, -16, v0
	v_add_u32_e32 v0, v12, v0
	v_and_b32_e32 v3, 3, v12
	v_lshrrev_b32_e32 v4, 2, v0
	v_lshlrev_b32_e32 v5, 1, v0
	v_and_or_b32 v3, v0, s2, v3
	v_and_b32_e32 v4, 4, v4
	v_and_b32_e32 v5, 24, v5
	v_or3_b32 v3, v3, v4, v5
	v_mul_i32_i24_e32 v5, 64, v12
	s_ashr_i32 s4, s1, 6
	v_sub_u32_e32 v1, v1, v5
	s_ashr_i32 s85, s84, 31
	s_ashr_i32 s5, s1, 8
	s_lshl_b32 s6, s4, 10
	v_lshlrev_b32_e32 v4, 5, v13
	v_ashrrev_i16_sdwa v1, v2, sext(v1) dst_sel:DWORD dst_unused:UNUSED_PAD src0_sel:DWORD src1_sel:BYTE_0
	s_lshl_b64 s[8:9], s[84:85], 10
	s_lshl_b64 s[2:3], s[84:85], 18
	v_and_b32_e32 v4, 32, v4
	v_bfe_i32 v14, v1, 0, 16
	s_add_u32 s16, s88, s2
	v_readlane_b32 s2, v255, 35
	v_add_lshl_u32 v1, v4, v14, 1
	s_addc_u32 s17, s2, s3
	s_add_i32 s2, s6, 0
	v_lshl_add_u32 v64, v3, 10, v1
	s_add_i32 m0, s2, 0x10000
	v_lshl_add_u32 v70, v0, 13, v1
	s_barrier
	global_load_lds_dwordx4 v64, s[16:17]
	s_add_i32 m0, s2, 0x12000
	s_add_u32 s3, s82, 0x3036f300
	s_addc_u32 s10, s83, 0
	s_add_u32 s14, s3, s8
	global_load_lds_dwordx4 v66, s[16:17]
	s_addc_u32 s15, s10, s9
	s_mov_b32 m0, s2
	s_add_i32 s11, s2, 0x2000
	global_load_lds_dwordx4 v70, s[14:15]
	s_mov_b32 m0, s11
	s_add_u32 s8, s16, 0x20000
	global_load_lds_dwordx4 v68, s[14:15]
	s_addc_u32 s9, s17, 0
	s_add_i32 m0, s2, 0x14000
	v_mov_b32_e32 v67, v65
	global_load_lds_dwordx4 v64, s[8:9]
	s_add_i32 m0, s2, 0x16000
	v_mov_b32_e32 v71, v65
	global_load_lds_dwordx4 v66, s[8:9]
	s_add_u32 s8, s14, 0x100000
	s_addc_u32 s9, s15, 0
	s_add_i32 s20, s2, 0x4000
	s_mov_b32 m0, s20
	s_add_i32 s22, s2, 0x6000
	global_load_lds_dwordx4 v70, s[8:9]
	s_mov_b32 m0, s22
	v_mov_b32_e32 v69, v65
	global_load_lds_dwordx4 v68, s[8:9]
	s_mov_b32 s23, 0
	v_lshl_add_u64 v[6:7], s[16:17], 0, v[64:65]
	v_lshl_add_u64 v[4:5], s[16:17], 0, v[66:67]
	v_lshl_add_u64 v[2:3], s[14:15], 0, v[70:71]
	s_cmp_lg_u32 s5, 1
	v_lshl_add_u64 v[0:1], s[14:15], 0, v[68:69]
	s_cbranch_scc1 .LBB0_2628
	s_barrier

.LBB0_2688:
	s_or_b64 exec, exec, s[4:5]
	s_waitcnt lgkmcnt(0)
	v_mov_b32_e32 v0, 0
	v_readlane_b32 s4, v255, 16
	v_mbcnt_lo_u32_b32 v0, -1, v0
	v_mbcnt_hi_u32_b32 v0, -1, v0
	v_add_u32_e32 v1, s33, v0
	v_readlane_b32 s5, v255, 17
	s_and_b64 vcc, exec, s[4:5]
	v_readfirstlane_b32 s3, v1
	s_cbranch_vccz .LBB0_2691
	s_and_b32 s1, s84, 0x7fffffe0
	s_mov_b64 s[12:13], 0
	s_cmpk_lg_i32 s1, 0x100
	s_mov_b64 s[8:9], 0
	s_cbranch_scc1 .LBB0_2692
	s_and_b32 s6, s84, 3
	s_bfe_u32 s4, s84, 0x30002
	s_mov_b32 s14, 64
	s_mov_b64 s[8:9], -1
	s_branch .LBB0_2692

.LBB0_2698:
	s_andn2_b64 vcc, exec, s[8:9]
	s_cbranch_vccz .Lmy_bsk19
	s_barrier
	s_branch .LBB0_2751
.Lmy_bsk19:
	v_ashrrev_i32_e32 v2, 31, v1
	v_lshrrev_b32_e32 v2, 26, v2
	v_add_u32_e32 v2, v1, v2
	v_ashrrev_i32_e32 v10, 6, v2
	v_bfe_i32 v2, v1, 27, 1
	v_lshlrev_b32_e32 v0, 4, v1
	v_lshrrev_b32_e32 v2, 22, v2
	v_add_u32_e32 v2, v0, v2
	v_and_b32_e32 v2, 0xfffffc00, v2
	v_sub_u32_e32 v2, v0, v2
	v_lshrrev_b32_e32 v3, 4, v2
	v_bitop3_b32 v3, v3, v2, 32 bitop3:0x6c
	v_ashrrev_i32_e32 v2, 31, v2
	v_lshrrev_b32_e32 v2, 26, v2
	v_add_u32_e32 v2, v3, v2
	v_ashrrev_i32_e32 v11, 6, v2
	v_lshlrev_b32_e32 v4, 3, v10
	v_mul_i32_i24_e32 v5, 64, v11
	v_and_b32_e32 v4, -16, v4
	v_sub_u32_e32 v3, v3, v5
	v_mov_b32_e32 v5, 1
	v_add_u32_e32 v2, v11, v4
	v_lshlrev_b32_e32 v4, 5, v10
	v_ashrrev_i16_sdwa v3, v5, sext(v3) dst_sel:DWORD dst_unused:UNUSED_PAD src0_sel:DWORD src1_sel:BYTE_0
	v_and_b32_e32 v4, 32, v4
	v_bfe_i32 v12, v3, 0, 16
	v_and_b32_e32 v7, 3, v11
	s_mov_b32 s1, 0xfffe0
	v_add_lshl_u32 v4, v4, v12, 1
	v_add_u32_e32 v0, 0x2000, v0
	v_lshlrev_b32_e32 v3, 1, v2
	v_lshrrev_b32_e32 v6, 2, v2
	v_and_or_b32 v7, v2, s1, v7
	v_lshl_add_u32 v196, v2, 12, v4
	v_ashrrev_i32_e32 v2, 31, v0
	v_lshrrev_b32_e32 v2, 22, v2
	v_add_u32_e32 v2, v0, v2
	v_ashrrev_i32_e32 v13, 10, v2
	v_mul_i32_i24_e32 v2, 0x400, v13
	v_sub_u32_e32 v0, v0, v2
	v_and_b32_e32 v3, 24, v3
	v_and_b32_e32 v6, 4, v6
	v_lshrrev_b32_e32 v2, 4, v0
	v_or3_b32 v3, v7, v6, v3
	v_bitop3_b32 v0, v2, v0, 32 bitop3:0x6c
	s_add_u32 s10, s82, 0x6767300
	v_lshl_add_u32 v198, v3, 12, v4
	v_ashrrev_i32_e32 v3, 31, v0
	s_addc_u32 s11, s83, 0
	s_ashr_i32 s2, s3, 6
	v_lshrrev_b32_e32 v3, 26, v3
	v_add_u32_e32 v3, v0, v3
	s_ashr_i32 s8, s3, 8
	s_lshl_b32 s40, s2, 10
	v_lshlrev_b32_e32 v2, 3, v13
	v_ashrrev_i32_e32 v14, 6, v3
	v_and_b32_e32 v3, 0xc0, v3
	s_cmp_eq_u32 s14, 64
	v_and_b32_e32 v2, -16, v2
	v_sub_u32_e32 v0, v0, v3
	s_cselect_b64 s[12:13], -1, 0
	v_add_u32_e32 v2, v14, v2
	v_ashrrev_i16_sdwa v0, v5, sext(v0) dst_sel:DWORD dst_unused:UNUSED_PAD src0_sel:DWORD src1_sel:BYTE_0
	v_and_b32_e32 v5, 3, v14
	s_and_b64 s[16:17], s[12:13], exec
	v_and_or_b32 v5, v2, s1, v5
	s_cselect_b32 s1, 4, 32
	s_ashr_i32 s5, s4, 31
	s_ashr_i32 s7, s6, 31
	s_ashr_i32 s15, s14, 31
	s_lshl_b64 s[16:17], s[4:5], 9
	s_lshl_b64 s[18:19], s[6:7], 20
	s_add_u32 s5, s10, s18
	s_addc_u32 s7, s11, s19
	s_add_u32 s36, s5, s16
	s_addc_u32 s37, s7, s17
	s_add_i32 s7, s40, 0
	s_add_i32 m0, s7, 0x10000
	s_lshl_b64 s[18:19], s[14:15], 20
	s_barrier
	global_load_lds_dwordx4 v198, s[36:37]
	s_add_i32 m0, s7, 0x12000
	v_lshlrev_b32_e32 v4, 5, v13
	v_bfe_i32 v15, v0, 0, 16
	v_lshlrev_b32_e32 v0, 1, v2
	v_lshrrev_b32_e32 v3, 2, v2
	s_add_u32 s5, s42, s18
	v_and_b32_e32 v4, 32, v4
	v_and_b32_e32 v0, 24, v0
	v_and_b32_e32 v3, 4, v3
	s_addc_u32 s9, s43, s19
	v_or3_b32 v0, v5, v3, v0
	v_add_lshl_u32 v3, v4, v15, 1
	s_add_u32 s34, s5, s16
	v_lshl_add_u32 v202, v0, 12, v3
	s_addc_u32 s35, s9, s17
	s_add_i32 s41, s7, 0x2000
	global_load_lds_dwordx4 v202, s[36:37]
	s_mov_b32 m0, s7
	s_add_u32 s16, s36, 0x80000
	v_lshl_add_u32 v200, v2, 12, v3
	global_load_lds_dwordx4 v196, s[34:35]
	s_mov_b32 m0, s41
	s_addc_u32 s17, s37, 0
	s_add_i32 s52, s7, 0x14000
	global_load_lds_dwordx4 v200, s[34:35]
	s_mov_b32 m0, s52
	s_add_i32 s53, s7, 0x16000
	global_load_lds_dwordx4 v198, s[16:17]
	s_mov_b32 m0, s53
	v_mov_b32_e32 v0, 0
	global_load_lds_dwordx4 v202, s[16:17]
	s_add_u32 s16, s34, 0x80000
	s_addc_u32 s17, s35, 0
	s_add_i32 s54, s7, 0x4000
	s_mov_b32 m0, s54
	s_add_i32 s55, s7, 0x6000
	global_load_lds_dwordx4 v196, s[16:17]
	s_mov_b32 m0, s55
	v_mov_b32_e32 v199, v0
	global_load_lds_dwordx4 v200, s[16:17]
	v_mov_b32_e32 v203, v0
	v_mov_b32_e32 v197, v0
	v_mov_b32_e32 v201, v0
	s_mov_b32 s15, 0
	v_lshl_add_u64 v[8:9], s[36:37], 0, v[198:199]
	v_lshl_add_u64 v[6:7], s[36:37], 0, v[202:203]
	v_lshl_add_u64 v[4:5], s[34:35], 0, v[196:197]
	s_cmp_lg_u32 s8, 1
	v_lshl_add_u64 v[2:3], s[34:35], 0, v[200:201]
	s_cbranch_scc1 .LBB0_2701
	s_barrier

.Lmy_bsk20:
	v_readlane_b32 s6, v255, 13
	s_lshl_b32 s4, s0, 3
	s_ashr_i32 s3, s2, 31
	s_ashr_i32 s5, s6, 31
	s_add_u32 s10, s2, s6
	s_addc_u32 s11, s3, s5
	s_lshl_b64 s[2:3], s[10:11], 2
	v_and_b32_e32 v2, 63, v20
	s_add_u32 s2, s2, 0x64e00
	v_lshlrev_b32_e32 v0, 2, v2
	s_addc_u32 s3, s3, 0
	s_lshl_b64 s[10:11], s[10:11], 12
	v_xor_b32_e32 v22, 0x80, v0
	v_xor_b32_e32 v23, 64, v0
	v_xor_b32_e32 v24, 32, v0
	v_xor_b32_e32 v25, 16, v0
	v_xor_b32_e32 v26, 8, v0
	v_xor_b32_e32 v27, 4, v0
	v_lshl_or_b32 v0, v2, 4, s10
	s_add_i32 s10, s1, 0x4000
	v_mov_b32_e32 v1, s11
	s_ashr_i32 s11, s10, 31
	s_ashr_i32 s5, s4, 31
	s_lshl_b64 s[10:11], s[10:11], 11
	v_cmp_eq_u32_e64 s[8:9], 0, v2
	s_lshl_b64 s[6:7], s[4:5], 2
	s_lshl_b64 s[12:13], s[4:5], 12
	v_lshl_or_b32 v2, v2, 3, s10
	v_mov_b32_e32 v3, s11
	s_lshl_b64 s[14:15], s[4:5], 11
	s_barrier
	s_branch .LBB0_2806

.Lmy_bsk21:
	s_ashr_i32 s14, s3, 8
	s_lshl_b32 s2, s14, 6
	s_add_u32 s4, s82, 0x54e00
	s_addc_u32 s5, s83, 0
	s_cmp_eq_u32 s22, 64
	s_cselect_b64 s[12:13], -1, 0
	s_cmp_lg_u32 s22, 64
	s_cselect_b64 s[6:7], -1, 0
	s_lshl_b32 s8, s22, 8
	v_and_b32_e32 v11, 15, v10
	s_add_i32 s8, s8, s2
	v_or_b32_e32 v0, s8, v11
	v_ashrrev_i32_e32 v1, 31, v0
	s_mov_b32 s1, 16
	v_lshl_add_u64 v[0:1], v[0:1], 2, s[4:5]
	s_barrier
	global_load_dword v233, v[0:1], off
	global_load_dword v232, v[0:1], off offset:64
	global_load_dword v231, v[0:1], off offset:128
	global_load_dword v230, v[0:1], off offset:192
	v_mov_b32_e32 v228, 1.0
	s_and_b64 vcc, exec, s[12:13]
	v_mov_b32_e32 v229, 1.0
	s_cbranch_vccnz .LBB0_2874
	global_load_dword v229, v[0:1], off offset:512
	v_cndmask_b32_e64 v2, 0, 1, s[6:7]
	v_cmp_ne_u32_e64 s[8:9], 1, v2
	s_andn2_b64 vcc, exec, s[6:7]
	s_cbranch_vccz .LBB0_2875

.Lmy_bsk22:
	v_ashrrev_i32_e32 v2, 31, v1
	v_lshrrev_b32_e32 v2, 26, v2
	v_add_u32_e32 v2, v1, v2
	v_ashrrev_i32_e32 v10, 6, v2
	v_bfe_i32 v2, v1, 27, 1
	v_lshlrev_b32_e32 v0, 4, v1
	v_lshrrev_b32_e32 v2, 22, v2
	v_add_u32_e32 v2, v0, v2
	v_and_b32_e32 v2, 0xfffffc00, v2
	v_sub_u32_e32 v2, v0, v2
	v_lshrrev_b32_e32 v3, 4, v2
	v_bitop3_b32 v3, v3, v2, 32 bitop3:0x6c
	v_ashrrev_i32_e32 v2, 31, v2
	v_lshrrev_b32_e32 v2, 26, v2
	v_lshlrev_b32_e32 v4, 3, v10
	v_add_u32_e32 v2, v3, v2
	v_and_b32_e32 v4, -16, v4
	v_ashrrev_i32_e32 v12, 6, v2
	v_add_u32_e32 v2, v12, v4
	v_lshlrev_b32_e32 v4, 5, v10
	v_and_b32_e32 v11, 32, v4
	v_mul_i32_i24_e32 v4, 64, v12
	v_sub_u32_e32 v3, v3, v4
	v_mov_b32_e32 v4, 1
	v_ashrrev_i16_sdwa v3, v4, sext(v3) dst_sel:DWORD dst_unused:UNUSED_PAD src0_sel:DWORD src1_sel:BYTE_0
	v_lshlrev_b32_e32 v5, 1, v2
	v_lshrrev_b32_e32 v6, 2, v2
	v_and_b32_e32 v7, 3, v12
	s_mov_b32 s2, 0xffffe0
	v_bfe_i32 v13, v3, 0, 16
	v_and_b32_e32 v5, 24, v5
	v_and_b32_e32 v6, 4, v6
	v_and_or_b32 v7, v2, s2, v7
	s_movk_i32 s6, 0xb00
	v_add_u32_e32 v3, v11, v13
	v_or3_b32 v5, v7, v6, v5
	v_mul_lo_u32 v2, v2, s6
	v_add_lshl_u32 v196, v3, v2, 1
	v_mul_u32_u24_e32 v2, 0xb00, v5
	v_add_u32_e32 v0, 0x2000, v0
	v_add_lshl_u32 v198, v2, v3, 1
	v_ashrrev_i32_e32 v2, 31, v0
	v_lshrrev_b32_e32 v2, 22, v2
	v_add_u32_e32 v2, v0, v2
	v_ashrrev_i32_e32 v14, 10, v2
	v_mul_i32_i24_e32 v2, 0x400, v14
	v_sub_u32_e32 v0, v0, v2
	v_lshrrev_b32_e32 v2, 4, v0
	s_add_u32 s30, s82, 0x5067300
	v_bitop3_b32 v0, v2, v0, 32 bitop3:0x6c
	s_addc_u32 s31, s83, 0
	s_ashr_i32 s8, s3, 6
	v_ashrrev_i32_e32 v3, 31, v0
	v_lshrrev_b32_e32 v3, 26, v3
	s_ashr_i32 s9, s3, 8
	s_lshl_b32 s34, s8, 10
	v_lshlrev_b32_e32 v2, 3, v14
	v_add_u32_e32 v3, v0, v3
	s_cmp_eq_u32 s1, 64
	v_and_b32_e32 v2, -16, v2
	v_ashrrev_i32_e32 v15, 6, v3
	v_lshlrev_b32_e32 v5, 5, v14
	s_cselect_b64 s[12:13], -1, 0
	v_add_u32_e32 v2, v15, v2
	v_and_b32_e32 v16, 32, v5
	v_and_b32_e32 v5, 3, v15
	s_and_b64 s[10:11], s[12:13], exec
	v_and_or_b32 v5, v2, s2, v5
	s_cselect_b32 s2, 4, 44
	s_ashr_i32 s5, s4, 31
	s_lshl_b64 s[10:11], s[4:5], 9
	s_mul_i32 s7, s35, 0x160000
	s_mul_hi_i32 s5, s35, 0x160000
	s_add_u32 s7, s30, s7
	s_addc_u32 s5, s31, s5
	s_add_u32 s26, s7, s10
	v_and_b32_e32 v3, 0xc0, v3
	s_addc_u32 s27, s5, s11
	s_add_i32 s36, s34, 0
	v_sub_u32_e32 v0, v0, v3
	s_add_i32 m0, s36, 0x10000
	v_ashrrev_i16_sdwa v0, v4, sext(v0) dst_sel:DWORD dst_unused:UNUSED_PAD src0_sel:DWORD src1_sel:BYTE_0
	v_lshlrev_b32_e32 v3, 1, v2
	v_lshrrev_b32_e32 v4, 2, v2
	s_barrier
	global_load_lds_dwordx4 v198, s[26:27]
	s_add_i32 m0, s36, 0x12000
	s_mul_i32 s7, s1, 0x160000
	v_readlane_b32 s14, v255, 18
	v_bfe_i32 v17, v0, 0, 16
	v_and_b32_e32 v3, 24, v3
	v_and_b32_e32 v4, 4, v4
	s_mul_hi_i32 s5, s1, 0x160000
	v_readlane_b32 s15, v255, 19
	s_add_u32 s7, s14, s7
	v_add_u32_e32 v0, v16, v17
	v_or3_b32 v3, v5, v4, v3
	v_mul_lo_u32 v2, v2, s6
	s_addc_u32 s5, s15, s5
	v_add_lshl_u32 v200, v0, v2, 1
	v_mul_u32_u24_e32 v2, 0xb00, v3
	s_add_u32 s22, s7, s10
	v_add_lshl_u32 v202, v2, v0, 1
	s_addc_u32 s23, s5, s11
	s_add_i32 s37, s36, 0x2000
	global_load_lds_dwordx4 v202, s[26:27]
	s_mov_b32 m0, s36
	s_add_u32 s10, s26, 0xb0000
	global_load_lds_dwordx4 v196, s[22:23]
	s_mov_b32 m0, s37
	s_addc_u32 s11, s27, 0
	s_add_i32 s38, s36, 0x14000
	global_load_lds_dwordx4 v200, s[22:23]
	s_mov_b32 m0, s38
	s_add_i32 s39, s36, 0x16000
	global_load_lds_dwordx4 v198, s[10:11]
	s_mov_b32 m0, s39
	v_mov_b32_e32 v0, 0
	global_load_lds_dwordx4 v202, s[10:11]
	s_add_u32 s10, s22, 0xb0000
	s_addc_u32 s11, s23, 0
	s_add_i32 s40, s36, 0x4000
	s_mov_b32 m0, s40
	s_add_i32 s41, s36, 0x6000
	global_load_lds_dwordx4 v196, s[10:11]
	s_mov_b32 m0, s41
	v_mov_b32_e32 v199, v0
	global_load_lds_dwordx4 v200, s[10:11]
	v_mov_b32_e32 v203, v0
	v_mov_b32_e32 v197, v0
	v_mov_b32_e32 v201, v0
	s_mov_b32 s7, 0
	v_lshl_add_u64 v[8:9], s[26:27], 0, v[198:199]
	v_lshl_add_u64 v[6:7], s[26:27], 0, v[202:203]
	v_lshl_add_u64 v[4:5], s[22:23], 0, v[196:197]
	s_cmp_lg_u32 s9, 1
	v_lshl_add_u64 v[2:3], s[22:23], 0, v[200:201]
	s_cbranch_scc1 .LBB0_2989
	s_barrier

.Lmy_bsk23:
	v_readlane_b32 s6, v255, 13
	s_lshl_b32 s4, s0, 3
	s_ashr_i32 s3, s2, 31
	s_ashr_i32 s5, s6, 31
	s_add_u32 s10, s2, s6
	s_addc_u32 s11, s3, s5
	s_lshl_b64 s[2:3], s[10:11], 2
	s_add_u32 s2, s2, 0x75200
	s_addc_u32 s3, s3, 0
	s_add_i32 s12, s1, 0x4000
	v_and_b32_e32 v2, 63, v32
	s_ashr_i32 s13, s12, 31
	v_lshlrev_b32_e32 v0, 2, v2
	s_ashr_i32 s5, s4, 31
	s_lshl_b64 s[10:11], s[10:11], 12
	s_lshl_b64 s[12:13], s[12:13], 11
	v_cmp_eq_u32_e64 s[8:9], 0, v2
	v_xor_b32_e32 v34, 0x80, v0
	v_xor_b32_e32 v35, 64, v0
	v_xor_b32_e32 v36, 32, v0
	v_xor_b32_e32 v37, 16, v0
	v_xor_b32_e32 v38, 8, v0
	v_xor_b32_e32 v39, 4, v0
	s_lshl_b64 s[6:7], s[4:5], 2
	v_lshl_or_b32 v0, v2, 4, s10
	v_mov_b32_e32 v1, s11
	s_lshl_b64 s[10:11], s[4:5], 12
	v_lshl_or_b32 v2, v2, 3, s12
	v_mov_b32_e32 v3, s13
	s_lshl_b64 s[12:13], s[4:5], 11
	s_barrier
	s_branch .LBB0_3098

.LBB0_3155:
	s_or_b64 exec, exec, s[4:5]
	s_waitcnt lgkmcnt(0)
	v_mov_b32_e32 v0, 0
	s_cmpk_lt_i32 s84, 0x82
	v_mbcnt_lo_u32_b32 v0, -1, v0
	v_mbcnt_hi_u32_b32 v0, -1, v0
	v_add_u32_e32 v10, s33, v0
	s_cselect_b64 s[6:7], -1, 0
	s_cmpk_gt_i32 s84, 0x81
	v_readfirstlane_b32 s3, v10
	s_cbranch_scc1 .LBB0_3161
	s_ashr_i32 s1, s84, 31
	s_lshr_b32 s1, s1, 29
	s_add_i32 s1, s84, s1
	s_and_b32 s2, s1, -8
	s_sub_i32 s2, s84, s2
	s_cmp_gt_i32 s2, 1
	s_cbranch_scc0 .LBB0_3158
	s_lshl_b32 s4, s2, 4
	s_or_b32 s8, s4, 2
	s_cbranch_execz .LBB0_3159
	s_branch .LBB0_3160

.Lmy_bsk24:
	s_ashr_i32 s14, s3, 8
	s_lshl_b32 s2, s14, 6
	s_add_u32 s6, s82, 0x65200
	s_addc_u32 s7, s83, 0
	s_cmp_eq_u32 s4, 64
	s_cselect_b64 s[12:13], -1, 0
	s_cmp_lg_u32 s4, 64
	s_cselect_b64 s[10:11], -1, 0
	s_lshl_b32 s5, s4, 8
	v_and_b32_e32 v11, 15, v10
	s_add_i32 s5, s5, s2
	v_or_b32_e32 v0, s5, v11
	v_ashrrev_i32_e32 v1, 31, v0
	s_mov_b32 s1, 16
	v_lshl_add_u64 v[0:1], v[0:1], 2, s[6:7]
	s_barrier
	global_load_dword v235, v[0:1], off
	global_load_dword v234, v[0:1], off offset:64
	global_load_dword v233, v[0:1], off offset:128
	global_load_dword v232, v[0:1], off offset:192
	v_mov_b32_e32 v230, 1.0
	s_and_b64 vcc, exec, s[12:13]
	v_mov_b32_e32 v231, 1.0
	s_cbranch_vccnz .LBB0_3166
	global_load_dword v231, v[0:1], off offset:512
	v_cndmask_b32_e64 v2, 0, 1, s[10:11]
	v_cmp_ne_u32_e64 s[8:9], 1, v2
	s_andn2_b64 vcc, exec, s[10:11]
	s_cbranch_vccz .LBB0_3167

.LBB0_3419:
	s_or_b64 exec, exec, s[4:5]
	s_waitcnt lgkmcnt(0)
	v_mov_b32_e32 v0, 0
	v_readlane_b32 s4, v255, 52
	v_mbcnt_lo_u32_b32 v0, -1, v0
	v_mbcnt_hi_u32_b32 v0, -1, v0
	v_add_u32_e32 v1, s33, v0
	v_readlane_b32 s5, v255, 53
	s_and_b64 vcc, exec, s[4:5]
	v_readfirstlane_b32 s3, v1
	s_cbranch_vccz .LBB0_3422
	s_mov_b64 s[6:7], 0
	s_cmpk_gt_u32 s84, 0x313
	s_mov_b64 s[4:5], 0
	s_cbranch_scc1 .LBB0_3423
	s_add_i32 s1, s84, 0xfffffd00
	s_mov_b32 s2, 64
	s_mov_b64 s[4:5], -1
	s_branch .LBB0_3423

.Lmy_bsk25:
	v_ashrrev_i32_e32 v2, 31, v1
	v_lshrrev_b32_e32 v2, 26, v2
	v_add_u32_e32 v2, v1, v2
	v_ashrrev_i32_e32 v10, 6, v2
	v_bfe_i32 v2, v1, 27, 1
	v_lshlrev_b32_e32 v0, 4, v1
	v_lshrrev_b32_e32 v2, 22, v2
	v_add_u32_e32 v2, v0, v2
	v_and_b32_e32 v2, 0xfffffc00, v2
	v_sub_u32_e32 v2, v0, v2
	v_lshrrev_b32_e32 v3, 4, v2
	v_bitop3_b32 v3, v3, v2, 32 bitop3:0x6c
	v_ashrrev_i32_e32 v2, 31, v2
	v_lshrrev_b32_e32 v2, 26, v2
	v_lshlrev_b32_e32 v4, 3, v10
	v_add_u32_e32 v2, v3, v2
	v_and_b32_e32 v4, -16, v4
	v_ashrrev_i32_e32 v12, 6, v2
	v_add_u32_e32 v2, v12, v4
	v_lshlrev_b32_e32 v4, 5, v10
	v_and_b32_e32 v11, 32, v4
	v_mul_i32_i24_e32 v4, 64, v12
	v_sub_u32_e32 v3, v3, v4
	v_mov_b32_e32 v4, 1
	v_ashrrev_i16_sdwa v3, v4, sext(v3) dst_sel:DWORD dst_unused:UNUSED_PAD src0_sel:DWORD src1_sel:BYTE_0
	v_lshlrev_b32_e32 v5, 1, v2
	v_lshrrev_b32_e32 v6, 2, v2
	v_and_b32_e32 v7, 3, v12
	s_mov_b32 s4, 0x1ffffe0
	v_bfe_i32 v13, v3, 0, 16
	v_and_b32_e32 v5, 24, v5
	v_and_b32_e32 v6, 4, v6
	v_and_or_b32 v7, v2, s4, v7
	s_movk_i32 s9, 0x180
	v_add_u32_e32 v3, v11, v13
	v_or3_b32 v5, v7, v6, v5
	v_mul_lo_u32 v2, v2, s9
	v_add_lshl_u32 v196, v3, v2, 1
	v_mul_lo_u32 v2, v5, s9
	v_add_u32_e32 v0, 0x2000, v0
	v_add_lshl_u32 v198, v2, v3, 1
	v_ashrrev_i32_e32 v2, 31, v0
	v_lshrrev_b32_e32 v2, 22, v2
	v_add_u32_e32 v2, v0, v2
	v_ashrrev_i32_e32 v14, 10, v2
	v_mul_i32_i24_e32 v2, 0x400, v14
	v_sub_u32_e32 v0, v0, v2
	s_add_u32 s24, s82, 0x6bc3f300
	v_lshrrev_b32_e32 v2, 4, v0
	s_addc_u32 s25, s83, 0
	v_bitop3_b32 v0, v2, v0, 32 bitop3:0x6c
	s_add_u32 s26, s82, 0x61a7300
	v_ashrrev_i32_e32 v3, 31, v0
	s_addc_u32 s27, s83, 0
	v_lshrrev_b32_e32 v3, 26, v3
	s_ashr_i32 s6, s3, 6
	s_ashr_i32 s8, s3, 8
	v_lshlrev_b32_e32 v2, 3, v14
	v_add_u32_e32 v3, v0, v3
	s_lshl_b32 s28, s6, 10
	v_and_b32_e32 v2, -16, v2
	v_ashrrev_i32_e32 v15, 6, v3
	v_lshlrev_b32_e32 v5, 5, v14
	s_cmp_eq_u32 s2, 64
	v_add_u32_e32 v2, v15, v2
	v_and_b32_e32 v16, 32, v5
	v_and_b32_e32 v5, 3, v15
	s_cselect_b64 s[10:11], -1, 0
	v_and_or_b32 v5, v2, s4, v5
	s_and_b64 s[4:5], s[10:11], exec
	v_and_b32_e32 v3, 0xc0, v3
	s_cselect_b32 s5, s26, s24
	s_mul_i32 s14, s1, 0x30000
	v_sub_u32_e32 v0, v0, v3
	s_cselect_b32 s4, s27, s25
	s_mul_hi_i32 s13, s1, 0x30000
	s_add_u32 s20, s5, s14
	v_ashrrev_i16_sdwa v0, v4, sext(v0) dst_sel:DWORD dst_unused:UNUSED_PAD src0_sel:DWORD src1_sel:BYTE_0
	v_lshlrev_b32_e32 v3, 1, v2
	v_lshrrev_b32_e32 v4, 2, v2
	s_addc_u32 s21, s4, s13
	s_add_i32 s29, s28, 0
	s_mov_b32 s46, 6
	v_bfe_i32 v17, v0, 0, 16
	v_and_b32_e32 v3, 24, v3
	v_and_b32_e32 v4, 4, v4
	s_add_i32 m0, s29, 0x10000
	v_add_u32_e32 v0, v16, v17
	v_or3_b32 v3, v5, v4, v3
	v_mul_lo_u32 v2, v2, s9
	s_mul_i32 s12, s2, 0x30000
	s_barrier
	global_load_lds_dwordx4 v198, s[20:21]
	s_add_i32 m0, s29, 0x12000
	v_add_lshl_u32 v200, v0, v2, 1
	v_mul_lo_u32 v2, v3, s9
	s_mul_hi_i32 s7, s2, 0x30000
	s_add_u32 s4, s78, s12
	v_add_lshl_u32 v202, v2, v0, 1
	s_addc_u32 s5, s79, s7
	s_add_i32 s30, s29, 0x2000
	global_load_lds_dwordx4 v202, s[20:21]
	s_mov_b32 m0, s29
	s_add_u32 s12, s20, 0x18000
	global_load_lds_dwordx4 v196, s[4:5]
	s_mov_b32 m0, s30
	s_addc_u32 s13, s21, 0
	s_add_i32 s31, s29, 0x14000
	global_load_lds_dwordx4 v200, s[4:5]
	s_mov_b32 m0, s31
	s_add_i32 s34, s29, 0x16000
	global_load_lds_dwordx4 v198, s[12:13]
	s_mov_b32 m0, s34
	v_mov_b32_e32 v0, 0
	global_load_lds_dwordx4 v202, s[12:13]
	s_add_u32 s12, s4, 0x18000
	s_addc_u32 s13, s5, 0
	s_add_i32 s35, s29, 0x4000
	s_mov_b32 m0, s35
	s_add_i32 s36, s29, 0x6000
	global_load_lds_dwordx4 v196, s[12:13]
	s_mov_b32 m0, s36
	v_mov_b32_e32 v199, v0
	global_load_lds_dwordx4 v200, s[12:13]
	v_mov_b32_e32 v203, v0
	v_mov_b32_e32 v197, v0
	v_mov_b32_e32 v201, v0
	s_movk_i32 s37, 0xc0
	s_mov_b32 s38, 0
	v_lshl_add_u64 v[8:9], s[20:21], 0, v[198:199]
	v_lshl_add_u64 v[6:7], s[20:21], 0, v[202:203]
	v_lshl_add_u64 v[4:5], s[4:5], 0, v[196:197]
	s_cmp_lg_u32 s8, 1
	v_lshl_add_u64 v[2:3], s[4:5], 0, v[200:201]
	s_cbranch_scc1 .LBB0_3428
	s_barrier

.LBB0_3616:
	s_or_b64 exec, exec, s[4:5]
	v_readlane_b32 s2, v255, 50
	v_readlane_b32 s3, v255, 51
	s_mov_b64 s[4:5], -1
	s_and_b64 vcc, exec, s[2:3]
	v_writelane_b32 v255, s88, 26
	s_waitcnt lgkmcnt(0)
	s_cbranch_vccnz .Lmy_bsk27
	s_barrier
	s_branch .LBB0_3753
.Lmy_bsk27:
	s_and_b32 s1, s84, 0x7f
	s_mul_i32 s2, s1, 0x56
	s_lshr_b32 s2, s2, 8
	s_mul_i32 s2, s2, 3
	s_sub_i32 s1, s1, s2
	s_and_b32 s19, s1, 0xff
	s_add_u32 s65, s82, 0x2836f300
	s_addc_u32 s66, s83, 0
	s_add_u32 s6, s82, 0x3466f300
	s_addc_u32 s7, s83, 0
	s_add_u32 s48, s82, 0x34a6f300
	s_addc_u32 s49, s83, 0
	s_add_u32 s1, s82, 0x3800
	v_writelane_b32 v255, s1, 9
	s_addc_u32 s1, s83, 0
	s_add_u32 s69, s82, 0x359ff300
	s_addc_u32 s72, s83, 0
	s_add_u32 s73, s80, 0x5480000
	s_addc_u32 s74, s81, 0
	s_add_u32 s50, s82, 0x26277300
	s_addc_u32 s51, s83, 0
	s_add_u32 s75, s82, 0x35a00700
	s_addc_u32 s76, s83, 0
	s_ashr_i32 s85, s84, 31
	v_writelane_b32 v255, s1, 31
	s_lshl_b64 s[2:3], s[84:85], 3
	v_writelane_b32 v255, s2, 33
	s_ashr_i32 s1, s0, 31
	s_lshl_b64 s[54:55], s[0:1], 3
	v_writelane_b32 v255, s3, 34
	s_add_i32 s3, 0, 0x10000
	s_mov_b32 s2, s84
	v_writelane_b32 v255, s2, 24
	s_mov_b32 s77, 0
	s_movk_i32 s78, 0x180
	v_writelane_b32 v255, s3, 25
	v_mov_b32_e32 v1, 0
	s_mov_b32 s79, 0x2aaaaaab
	s_movk_i32 s85, 0xffe8
	s_movk_i32 s92, 0x280
	s_movk_i32 s93, 0x1800
	s_movk_i32 s94, 0x1000
	s_add_i32 s95, 0, 0x20800
	v_mov_b32_e32 v148, 0xa000
	v_mov_b32_e32 v149, 0x4000
	v_mov_b32_e32 v150, 0xf149f2ca
	v_mov_b32_e32 v151, 0x100
	s_mov_b32 s96, s84
	v_writelane_b32 v255, s19, 43
	s_cmp_lg_u32 s77, s19
	s_mov_b64 s[4:5], -1
	s_cbranch_scc0 .Lmy_bsk26
	s_barrier
	s_branch .LBB0_3653
.Lmy_bsk26:
	s_barrier
.LBB0_3618:
	s_andn2_b64 vcc, exec, s[4:5]
	s_cbranch_vccnz .LBB0_3702

.LBB0_3885:
	s_or_b64 exec, exec, s[4:5]
	s_waitcnt lgkmcnt(0)
	v_mov_b32_e32 v0, 0
	v_readlane_b32 s2, v255, 28
	v_mbcnt_lo_u32_b32 v0, -1, v0
	v_mbcnt_hi_u32_b32 v0, -1, v0
	v_add_u32_e32 v10, s33, v0
	v_readlane_b32 s3, v255, 29
	v_mov_b32_e32 v65, 0
	s_andn2_b64 vcc, exec, s[2:3]
	v_readfirstlane_b32 s1, v10
	s_cbranch_vccz .Lmy_bsk28
	s_barrier
	s_branch .LBB0_3896
.Lmy_bsk28:
	v_lshlrev_b32_e32 v0, 4, v10
	v_add_u32_e32 v1, 0x2000, v0
	v_ashrrev_i32_e32 v2, 31, v1
	v_lshrrev_b32_e32 v2, 22, v2
	v_add_u32_e32 v2, v1, v2
	v_ashrrev_i32_e32 v8, 10, v2
	v_mul_i32_i24_e32 v2, 0x400, v8
	v_sub_u32_e32 v1, v1, v2
	v_lshrrev_b32_e32 v2, 4, v1
	v_bitop3_b32 v1, v2, v1, 32 bitop3:0x6c
	v_ashrrev_i32_e32 v2, 31, v1
	v_lshrrev_b32_e32 v2, 26, v2
	v_add_u32_e32 v2, v1, v2
	v_lshlrev_b32_e32 v3, 3, v8
	v_ashrrev_i32_e32 v9, 6, v2
	v_and_b32_e32 v3, -16, v3
	v_add_u32_e32 v3, v9, v3
	v_and_b32_e32 v4, 3, v9
	s_mov_b32 s2, 0x3fffe0
	v_lshrrev_b32_e32 v5, 2, v3
	v_lshlrev_b32_e32 v6, 1, v3
	v_and_b32_e32 v2, 0xc0, v2
	v_and_or_b32 v4, v3, s2, v4
	v_and_b32_e32 v5, 4, v5
	v_and_b32_e32 v6, 24, v6
	v_sub_u32_e32 v1, v1, v2
	v_mov_b32_e32 v2, 1
	v_or3_b32 v4, v4, v5, v6
	v_lshlrev_b32_e32 v5, 5, v8
	v_ashrrev_i16_sdwa v1, v2, sext(v1) dst_sel:DWORD dst_unused:UNUSED_PAD src0_sel:DWORD src1_sel:BYTE_0
	v_and_b32_e32 v5, 32, v5
	v_bfe_i32 v11, v1, 0, 16
	v_add_lshl_u32 v1, v5, v11, 1
	v_lshl_add_u32 v66, v4, 10, v1
	v_lshl_add_u32 v68, v3, 13, v1
	v_bfe_i32 v1, v10, 27, 1
	v_lshrrev_b32_e32 v1, 22, v1
	v_add_u32_e32 v1, v0, v1
	v_and_b32_e32 v1, 0xfffffc00, v1
	v_sub_u32_e32 v0, v0, v1
	v_lshrrev_b32_e32 v1, 4, v0
	v_bitop3_b32 v1, v1, v0, 32 bitop3:0x6c
	v_ashrrev_i32_e32 v0, 31, v0
	v_lshrrev_b32_e32 v0, 26, v0
	v_add_u32_e32 v0, v1, v0
	v_ashrrev_i32_e32 v12, 6, v0
	v_ashrrev_i32_e32 v0, 31, v10
	v_lshrrev_b32_e32 v0, 26, v0
	v_add_u32_e32 v0, v10, v0
	v_ashrrev_i32_e32 v13, 6, v0
	v_lshlrev_b32_e32 v0, 3, v13
	v_and_b32_e32 v0, -16, v0
	v_add_u32_e32 v0, v12, v0
	v_and_b32_e32 v3, 3, v12
	v_lshrrev_b32_e32 v4, 2, v0
	v_lshlrev_b32_e32 v5, 1, v0
	v_and_or_b32 v3, v0, s2, v3
	v_and_b32_e32 v4, 4, v4
	v_and_b32_e32 v5, 24, v5
	v_or3_b32 v3, v3, v4, v5
	v_mul_i32_i24_e32 v5, 64, v12
	s_ashr_i32 s4, s1, 6
	v_sub_u32_e32 v1, v1, v5
	s_ashr_i32 s85, s84, 31
	s_ashr_i32 s5, s1, 8
	s_lshl_b32 s6, s4, 10
	v_lshlrev_b32_e32 v4, 5, v13
	v_ashrrev_i16_sdwa v1, v2, sext(v1) dst_sel:DWORD dst_unused:UNUSED_PAD src0_sel:DWORD src1_sel:BYTE_0
	s_lshl_b64 s[8:9], s[84:85], 10
	s_lshl_b64 s[2:3], s[84:85], 18
	v_and_b32_e32 v4, 32, v4
	v_bfe_i32 v14, v1, 0, 16
	s_add_u32 s14, s88, s2
	v_readlane_b32 s2, v255, 35
	v_add_lshl_u32 v1, v4, v14, 1
	s_addc_u32 s15, s2, s3
	s_add_i32 s2, s6, 0
	s_mov_b32 s22, 8
	v_lshl_add_u32 v64, v3, 10, v1
	s_add_i32 m0, s2, 0x10000
	v_lshl_add_u32 v70, v0, 13, v1
	s_barrier
	global_load_lds_dwordx4 v64, s[14:15]
	s_add_i32 m0, s2, 0x12000
	s_add_u32 s3, s82, 0x3036f300
	s_addc_u32 s18, s83, 0
	s_add_u32 s12, s3, s8
	global_load_lds_dwordx4 v66, s[14:15]
	s_addc_u32 s13, s18, s9
	s_mov_b32 m0, s2
	s_add_i32 s19, s2, 0x2000
	global_load_lds_dwordx4 v70, s[12:13]
	s_mov_b32 m0, s19
	s_add_u32 s8, s14, 0x20000
	global_load_lds_dwordx4 v68, s[12:13]
	s_addc_u32 s9, s15, 0
	s_add_i32 m0, s2, 0x14000
	v_mov_b32_e32 v67, v65
	global_load_lds_dwordx4 v64, s[8:9]
	s_add_i32 m0, s2, 0x16000
	v_mov_b32_e32 v71, v65
	global_load_lds_dwordx4 v66, s[8:9]
	s_add_u32 s8, s12, 0x100000
	s_addc_u32 s9, s13, 0
	s_add_i32 s20, s2, 0x4000
	s_mov_b32 m0, s20
	s_add_i32 s21, s2, 0x6000
	global_load_lds_dwordx4 v70, s[8:9]
	s_mov_b32 m0, s21
	v_mov_b32_e32 v69, v65
	global_load_lds_dwordx4 v68, s[8:9]
	s_mov_b32 s23, 0
	v_lshl_add_u64 v[6:7], s[14:15], 0, v[64:65]
	v_lshl_add_u64 v[4:5], s[14:15], 0, v[66:67]
	v_lshl_add_u64 v[2:3], s[12:13], 0, v[70:71]
	s_cmp_lg_u32 s5, 1
	v_lshl_add_u64 v[0:1], s[12:13], 0, v[68:69]
	s_cbranch_scc1 .LBB0_3888
	s_barrier

.LBB0_3948:
	s_or_b64 exec, exec, s[4:5]
	s_waitcnt lgkmcnt(0)
	v_mov_b32_e32 v0, 0
	v_readlane_b32 s4, v255, 16
	v_mbcnt_lo_u32_b32 v0, -1, v0
	v_mbcnt_hi_u32_b32 v0, -1, v0
	v_add_u32_e32 v1, s33, v0
	v_readlane_b32 s5, v255, 17
	s_and_b64 vcc, exec, s[4:5]
	v_readfirstlane_b32 s3, v1
	s_cbranch_vccz .LBB0_3951
	s_and_b32 s1, s84, 0x7fffffe0
	s_mov_b64 s[10:11], 0
	s_cmpk_lg_i32 s1, 0x100
	s_mov_b64 s[8:9], 0
	s_cbranch_scc1 .LBB0_3952
	s_bfe_u32 s4, s84, 0x30002
	s_and_b32 s6, s84, 3
	s_mov_b32 s12, 64
	s_mov_b64 s[8:9], -1
	s_branch .LBB0_3952

.Lmy_bsk29:
	v_ashrrev_i32_e32 v2, 31, v1
	v_lshrrev_b32_e32 v2, 26, v2
	v_add_u32_e32 v2, v1, v2
	v_ashrrev_i32_e32 v10, 6, v2
	v_bfe_i32 v2, v1, 27, 1
	v_lshlrev_b32_e32 v0, 4, v1
	v_lshrrev_b32_e32 v2, 22, v2
	v_add_u32_e32 v2, v0, v2
	v_and_b32_e32 v2, 0xfffffc00, v2
	v_sub_u32_e32 v2, v0, v2
	v_lshrrev_b32_e32 v3, 4, v2
	v_bitop3_b32 v3, v3, v2, 32 bitop3:0x6c
	v_ashrrev_i32_e32 v2, 31, v2
	v_lshrrev_b32_e32 v2, 26, v2
	v_add_u32_e32 v2, v3, v2
	v_ashrrev_i32_e32 v11, 6, v2
	v_lshlrev_b32_e32 v4, 3, v10
	v_mul_i32_i24_e32 v5, 64, v11
	v_and_b32_e32 v4, -16, v4
	v_sub_u32_e32 v3, v3, v5
	v_mov_b32_e32 v5, 1
	v_add_u32_e32 v2, v11, v4
	v_lshlrev_b32_e32 v4, 5, v10
	v_ashrrev_i16_sdwa v3, v5, sext(v3) dst_sel:DWORD dst_unused:UNUSED_PAD src0_sel:DWORD src1_sel:BYTE_0
	v_and_b32_e32 v4, 32, v4
	v_bfe_i32 v12, v3, 0, 16
	v_and_b32_e32 v7, 3, v11
	s_mov_b32 s1, 0xfffe0
	v_add_lshl_u32 v4, v4, v12, 1
	v_add_u32_e32 v0, 0x2000, v0
	v_lshlrev_b32_e32 v3, 1, v2
	v_lshrrev_b32_e32 v6, 2, v2
	v_and_or_b32 v7, v2, s1, v7
	v_lshl_add_u32 v196, v2, 12, v4
	v_ashrrev_i32_e32 v2, 31, v0
	v_lshrrev_b32_e32 v2, 22, v2
	v_add_u32_e32 v2, v0, v2
	v_ashrrev_i32_e32 v13, 10, v2
	v_mul_i32_i24_e32 v2, 0x400, v13
	v_sub_u32_e32 v0, v0, v2
	v_and_b32_e32 v3, 24, v3
	v_and_b32_e32 v6, 4, v6
	v_lshrrev_b32_e32 v2, 4, v0
	v_or3_b32 v3, v7, v6, v3
	v_bitop3_b32 v0, v2, v0, 32 bitop3:0x6c
	s_add_u32 s38, s82, 0x6b67300
	v_lshl_add_u32 v198, v3, 12, v4
	v_ashrrev_i32_e32 v3, 31, v0
	s_addc_u32 s39, s83, 0
	s_ashr_i32 s2, s3, 6
	v_lshrrev_b32_e32 v3, 26, v3
	v_add_u32_e32 v3, v0, v3
	s_ashr_i32 s8, s3, 8
	s_lshl_b32 s40, s2, 10
	v_lshlrev_b32_e32 v2, 3, v13
	v_ashrrev_i32_e32 v14, 6, v3
	v_and_b32_e32 v3, 0xc0, v3
	s_cmp_eq_u32 s12, 64
	v_and_b32_e32 v2, -16, v2
	v_sub_u32_e32 v0, v0, v3
	s_cselect_b64 s[10:11], -1, 0
	v_add_u32_e32 v2, v14, v2
	v_ashrrev_i16_sdwa v0, v5, sext(v0) dst_sel:DWORD dst_unused:UNUSED_PAD src0_sel:DWORD src1_sel:BYTE_0
	v_and_b32_e32 v5, 3, v14
	s_and_b64 s[14:15], s[10:11], exec
	v_and_or_b32 v5, v2, s1, v5
	s_cselect_b32 s1, 4, 32
	s_ashr_i32 s5, s4, 31
	s_ashr_i32 s7, s6, 31
	s_ashr_i32 s13, s12, 31
	s_lshl_b64 s[14:15], s[4:5], 9
	s_lshl_b64 s[16:17], s[6:7], 20
	s_add_u32 s5, s38, s16
	s_addc_u32 s7, s39, s17
	s_add_u32 s34, s5, s14
	s_addc_u32 s35, s7, s15
	s_add_i32 s7, s40, 0
	s_add_i32 m0, s7, 0x10000
	s_lshl_b64 s[16:17], s[12:13], 20
	s_barrier
	global_load_lds_dwordx4 v198, s[34:35]
	s_add_i32 m0, s7, 0x12000
	v_lshlrev_b32_e32 v4, 5, v13
	v_bfe_i32 v15, v0, 0, 16
	v_lshlrev_b32_e32 v0, 1, v2
	v_lshrrev_b32_e32 v3, 2, v2
	s_add_u32 s5, s42, s16
	v_and_b32_e32 v4, 32, v4
	v_and_b32_e32 v0, 24, v0
	v_and_b32_e32 v3, 4, v3
	s_addc_u32 s9, s43, s17
	v_or3_b32 v0, v5, v3, v0
	v_add_lshl_u32 v3, v4, v15, 1
	s_add_u32 s30, s5, s14
	v_lshl_add_u32 v202, v0, 12, v3
	s_addc_u32 s31, s9, s15
	s_add_i32 s41, s7, 0x2000
	global_load_lds_dwordx4 v202, s[34:35]
	s_mov_b32 m0, s7
	s_add_u32 s14, s34, 0x80000
	v_lshl_add_u32 v200, v2, 12, v3
	global_load_lds_dwordx4 v196, s[30:31]
	s_mov_b32 m0, s41
	s_addc_u32 s15, s35, 0
	s_add_i32 s44, s7, 0x14000
	global_load_lds_dwordx4 v200, s[30:31]
	s_mov_b32 m0, s44
	s_add_i32 s45, s7, 0x16000
	global_load_lds_dwordx4 v198, s[14:15]
	s_mov_b32 m0, s45
	v_mov_b32_e32 v0, 0
	global_load_lds_dwordx4 v202, s[14:15]
	s_add_u32 s14, s30, 0x80000
	s_addc_u32 s15, s31, 0
	s_add_i32 s46, s7, 0x4000
	s_mov_b32 m0, s46
	s_add_i32 s47, s7, 0x6000
	global_load_lds_dwordx4 v196, s[14:15]
	s_mov_b32 m0, s47
	v_mov_b32_e32 v199, v0
	global_load_lds_dwordx4 v200, s[14:15]
	v_mov_b32_e32 v203, v0
	v_mov_b32_e32 v197, v0
	v_mov_b32_e32 v201, v0
	s_mov_b32 s13, 0
	v_lshl_add_u64 v[8:9], s[34:35], 0, v[198:199]
	v_lshl_add_u64 v[6:7], s[34:35], 0, v[202:203]
	v_lshl_add_u64 v[4:5], s[30:31], 0, v[196:197]
	s_cmp_lg_u32 s8, 1
	v_lshl_add_u64 v[2:3], s[30:31], 0, v[200:201]
	s_cbranch_scc1 .LBB0_3961
	s_barrier

.LBB0_4063:
	s_or_b64 exec, exec, s[4:5]
	s_waitcnt lgkmcnt(0)
	v_mov_b32_e32 v0, 0
	v_mov_b32_e32 v23, 0
	v_mbcnt_lo_u32_b32 v0, -1, v0
	v_mbcnt_hi_u32_b32 v0, -1, v0
	v_add_u32_e32 v22, s33, v0
	s_nop 0
	v_readfirstlane_b32 s1, v22
	s_ashr_i32 s2, s1, 6
	v_readlane_b32 s1, v255, 13
	s_add_i32 s1, s2, s1
	s_cmpk_gt_i32 s1, 0x7f
	s_cbranch_scc0 .Lmy_bsk30
	s_barrier
	s_branch .LBB0_4068
.Lmy_bsk30:
	v_readlane_b32 s6, v255, 13
	s_lshl_b32 s4, s0, 3
	s_ashr_i32 s3, s2, 31
	s_ashr_i32 s5, s6, 31
	s_add_u32 s10, s2, s6
	s_addc_u32 s11, s3, s5
	s_lshl_b64 s[2:3], s[10:11], 2
	s_add_u32 s2, s2, 0x85600
	s_addc_u32 s3, s3, 0
	s_add_i32 s12, s1, 0x4000
	v_and_b32_e32 v2, 63, v22
	s_ashr_i32 s13, s12, 31
	v_lshlrev_b32_e32 v0, 2, v2
	s_ashr_i32 s5, s4, 31
	s_lshl_b64 s[10:11], s[10:11], 12
	s_lshl_b64 s[12:13], s[12:13], 11
	v_cmp_eq_u32_e64 s[8:9], 0, v2
	v_xor_b32_e32 v24, 0x80, v0
	v_xor_b32_e32 v25, 64, v0
	v_xor_b32_e32 v26, 32, v0
	v_xor_b32_e32 v27, 16, v0
	v_xor_b32_e32 v28, 8, v0
	v_xor_b32_e32 v29, 4, v0
	s_lshl_b64 s[6:7], s[4:5], 2
	v_lshl_or_b32 v0, v2, 4, s10
	v_mov_b32_e32 v1, s11
	s_lshl_b64 s[10:11], s[4:5], 12
	v_lshl_or_b32 v2, v2, 3, s12
	v_mov_b32_e32 v3, s13
	s_lshl_b64 s[12:13], s[4:5], 11
	s_barrier
	s_branch .LBB0_4066

.Lmy_bsk31:
	s_ashr_i32 s12, s3, 8
	s_lshl_b32 s2, s12, 6
	s_add_u32 s4, s82, 0x75600
	s_addc_u32 s5, s83, 0
	s_cmp_eq_u32 s20, 64
	s_cselect_b64 s[8:9], -1, 0
	s_cmp_lg_u32 s20, 64
	s_cselect_b64 s[10:11], -1, 0
	s_lshl_b32 s6, s20, 8
	v_and_b32_e32 v11, 15, v10
	s_add_i32 s6, s6, s2
	v_or_b32_e32 v0, s6, v11
	v_ashrrev_i32_e32 v1, 31, v0
	s_mov_b32 s1, 16
	v_lshl_add_u64 v[0:1], v[0:1], 2, s[4:5]
	s_barrier
	global_load_dword v233, v[0:1], off
	global_load_dword v232, v[0:1], off offset:64
	global_load_dword v231, v[0:1], off offset:128
	global_load_dword v230, v[0:1], off offset:192
	v_mov_b32_e32 v228, 1.0
	s_and_b64 vcc, exec, s[8:9]
	v_mov_b32_e32 v229, 1.0
	s_cbranch_vccnz .LBB0_4134
	global_load_dword v229, v[0:1], off offset:512
	v_cndmask_b32_e64 v2, 0, 1, s[10:11]
	v_cmp_ne_u32_e64 s[6:7], 1, v2
	s_andn2_b64 vcc, exec, s[10:11]
	s_cbranch_vccz .LBB0_4135

.LBB0_4227:
	s_or_b64 exec, exec, s[4:5]
	s_waitcnt lgkmcnt(0)
	v_mov_b32_e32 v0, 0
	v_readlane_b32 s4, v255, 16
	v_mbcnt_lo_u32_b32 v0, -1, v0
	v_mbcnt_hi_u32_b32 v0, -1, v0
	v_add_u32_e32 v1, s33, v0
	v_readlane_b32 s5, v255, 17
	s_and_b64 vcc, exec, s[4:5]
	v_readfirstlane_b32 s3, v1
	s_cbranch_vccz .LBB0_4230
	s_mov_b64 s[8:9], 0
	s_cmpk_gt_u32 s84, 0x12b
	s_mov_b64 s[6:7], 0
	s_cbranch_scc1 .LBB0_4231
	s_and_b32 s35, s84, 3
	s_bfe_u32 s4, s84, 0x40002
	s_mov_b32 s1, 64
	s_mov_b64 s[6:7], -1
	s_branch .LBB0_4231

.Lmy_bsk32:
	v_ashrrev_i32_e32 v2, 31, v1
	v_lshrrev_b32_e32 v2, 26, v2
	v_add_u32_e32 v2, v1, v2
	v_ashrrev_i32_e32 v10, 6, v2
	v_bfe_i32 v2, v1, 27, 1
	v_lshlrev_b32_e32 v0, 4, v1
	v_lshrrev_b32_e32 v2, 22, v2
	v_add_u32_e32 v2, v0, v2
	v_and_b32_e32 v2, 0xfffffc00, v2
	v_sub_u32_e32 v2, v0, v2
	v_lshrrev_b32_e32 v3, 4, v2
	v_bitop3_b32 v3, v3, v2, 32 bitop3:0x6c
	v_ashrrev_i32_e32 v2, 31, v2
	v_lshrrev_b32_e32 v2, 26, v2
	v_lshlrev_b32_e32 v4, 3, v10
	v_add_u32_e32 v2, v3, v2
	v_and_b32_e32 v4, -16, v4
	v_ashrrev_i32_e32 v12, 6, v2
	v_add_u32_e32 v2, v12, v4
	v_lshlrev_b32_e32 v4, 5, v10
	v_and_b32_e32 v11, 32, v4
	v_mul_i32_i24_e32 v4, 64, v12
	v_sub_u32_e32 v3, v3, v4
	v_mov_b32_e32 v4, 1
	v_ashrrev_i16_sdwa v3, v4, sext(v3) dst_sel:DWORD dst_unused:UNUSED_PAD src0_sel:DWORD src1_sel:BYTE_0
	v_lshlrev_b32_e32 v5, 1, v2
	v_lshrrev_b32_e32 v6, 2, v2
	v_and_b32_e32 v7, 3, v12
	s_mov_b32 s2, 0xffffe0
	v_bfe_i32 v13, v3, 0, 16
	v_and_b32_e32 v5, 24, v5
	v_and_b32_e32 v6, 4, v6
	v_and_or_b32 v7, v2, s2, v7
	s_movk_i32 s8, 0xb00
	v_add_u32_e32 v3, v11, v13
	v_or3_b32 v5, v7, v6, v5
	v_mul_lo_u32 v2, v2, s8
	v_add_lshl_u32 v196, v3, v2, 1
	v_mul_u32_u24_e32 v2, 0xb00, v5
	v_add_u32_e32 v0, 0x2000, v0
	v_add_lshl_u32 v198, v2, v3, 1
	v_ashrrev_i32_e32 v2, 31, v0
	v_lshrrev_b32_e32 v2, 22, v2
	v_add_u32_e32 v2, v0, v2
	v_ashrrev_i32_e32 v14, 10, v2
	v_mul_i32_i24_e32 v2, 0x400, v14
	v_sub_u32_e32 v0, v0, v2
	v_lshrrev_b32_e32 v2, 4, v0
	s_add_u32 s30, s82, 0x55e7300
	v_bitop3_b32 v0, v2, v0, 32 bitop3:0x6c
	s_addc_u32 s31, s83, 0
	s_ashr_i32 s6, s3, 6
	v_ashrrev_i32_e32 v3, 31, v0
	v_lshrrev_b32_e32 v3, 26, v3
	s_ashr_i32 s7, s3, 8
	s_lshl_b32 s34, s6, 10
	v_lshlrev_b32_e32 v2, 3, v14
	v_add_u32_e32 v3, v0, v3
	s_cmp_eq_u32 s1, 64
	v_and_b32_e32 v2, -16, v2
	v_ashrrev_i32_e32 v15, 6, v3
	v_lshlrev_b32_e32 v5, 5, v14
	s_cselect_b64 s[10:11], -1, 0
	v_add_u32_e32 v2, v15, v2
	v_and_b32_e32 v16, 32, v5
	v_and_b32_e32 v5, 3, v15
	s_and_b64 s[12:13], s[10:11], exec
	v_and_or_b32 v5, v2, s2, v5
	s_cselect_b32 s2, 4, 44
	s_ashr_i32 s5, s4, 31
	s_lshl_b64 s[12:13], s[4:5], 9
	s_mul_i32 s9, s35, 0x160000
	s_mul_hi_i32 s5, s35, 0x160000
	s_add_u32 s9, s30, s9
	s_addc_u32 s5, s31, s5
	s_add_u32 s26, s9, s12
	v_and_b32_e32 v3, 0xc0, v3
	s_addc_u32 s27, s5, s13
	s_add_i32 s36, s34, 0
	v_sub_u32_e32 v0, v0, v3
	s_add_i32 m0, s36, 0x10000
	v_ashrrev_i16_sdwa v0, v4, sext(v0) dst_sel:DWORD dst_unused:UNUSED_PAD src0_sel:DWORD src1_sel:BYTE_0
	v_lshlrev_b32_e32 v3, 1, v2
	v_lshrrev_b32_e32 v4, 2, v2
	s_barrier
	global_load_lds_dwordx4 v198, s[26:27]
	s_add_i32 m0, s36, 0x12000
	s_mul_i32 s9, s1, 0x160000
	v_readlane_b32 s14, v255, 18
	v_bfe_i32 v17, v0, 0, 16
	v_and_b32_e32 v3, 24, v3
	v_and_b32_e32 v4, 4, v4
	s_mul_hi_i32 s5, s1, 0x160000
	v_readlane_b32 s15, v255, 19
	s_add_u32 s9, s14, s9
	v_add_u32_e32 v0, v16, v17
	v_or3_b32 v3, v5, v4, v3
	v_mul_lo_u32 v2, v2, s8
	s_addc_u32 s5, s15, s5
	v_add_lshl_u32 v200, v0, v2, 1
	v_mul_u32_u24_e32 v2, 0xb00, v3
	s_add_u32 s22, s9, s12
	v_add_lshl_u32 v202, v2, v0, 1
	s_addc_u32 s23, s5, s13
	s_add_i32 s37, s36, 0x2000
	global_load_lds_dwordx4 v202, s[26:27]
	s_mov_b32 m0, s36
	s_add_u32 s12, s26, 0xb0000
	global_load_lds_dwordx4 v196, s[22:23]
	s_mov_b32 m0, s37
	s_addc_u32 s13, s27, 0
	s_add_i32 s38, s36, 0x14000
	global_load_lds_dwordx4 v200, s[22:23]
	s_mov_b32 m0, s38
	s_add_i32 s39, s36, 0x16000
	global_load_lds_dwordx4 v198, s[12:13]
	s_mov_b32 m0, s39
	v_mov_b32_e32 v0, 0
	global_load_lds_dwordx4 v202, s[12:13]
	s_add_u32 s12, s22, 0xb0000
	s_addc_u32 s13, s23, 0
	s_add_i32 s40, s36, 0x4000
	s_mov_b32 m0, s40
	s_add_i32 s41, s36, 0x6000
	global_load_lds_dwordx4 v196, s[12:13]
	s_mov_b32 m0, s41
	v_mov_b32_e32 v199, v0
	global_load_lds_dwordx4 v200, s[12:13]
	v_mov_b32_e32 v203, v0
	v_mov_b32_e32 v197, v0
	v_mov_b32_e32 v201, v0
	s_mov_b32 s13, 0
	v_lshl_add_u64 v[8:9], s[26:27], 0, v[198:199]
	v_lshl_add_u64 v[6:7], s[26:27], 0, v[202:203]
	v_lshl_add_u64 v[4:5], s[22:23], 0, v[196:197]
	s_cmp_lg_u32 s7, 1
	v_lshl_add_u64 v[2:3], s[22:23], 0, v[200:201]
	s_cbranch_scc1 .LBB0_4240
	s_barrier

.LBB0_4346:
	s_or_b64 exec, exec, s[2:3]
	s_waitcnt lgkmcnt(0)
	v_mov_b32_e32 v0, 0
	v_readlane_b32 s2, v255, 13
	v_mbcnt_lo_u32_b32 v0, -1, v0
	v_mbcnt_hi_u32_b32 v0, -1, v0
	v_add_u32_e32 v12, s33, v0
	s_mov_b32 s3, 0
	v_readfirstlane_b32 s1, v12
	s_ashr_i32 s1, s1, 6
	s_add_i32 s4, s1, s2
	v_mov_b32_e32 v1, 0
	s_mov_b32 s6, 0
	s_cmpk_gt_i32 s4, 0x407f
	s_cbranch_scc0 .Lmy_bsk33
	s_barrier
	s_branch .LBB0_4362
.Lmy_bsk33:
	s_ashr_i32 s7, s6, 31
	s_lshl_b64 s[6:7], s[6:7], 3
	v_readlane_b32 s8, v255, 2
	v_readlane_b32 s9, v255, 3
	s_add_u32 s6, s8, s6
	s_addc_u32 s7, s9, s7
	s_barrier
	s_load_dwordx2 s[6:7], s[6:7], 0xb8
	v_lshlrev_b32_e32 v4, 2, v12
	v_and_b32_e32 v14, 0xfc, v4
	v_readlane_b32 s8, v255, 39
	v_lshlrev_b32_e32 v0, 2, v14
	v_readlane_b32 s9, v255, 40
	s_movk_i32 s1, 0x80
	v_bfrev_b32_e32 v5, 0.5
	v_lshl_add_u64 v[2:3], s[8:9], 0, v[0:1]
	v_bitop3_b32 v30, v4, s1, v5 bitop3:0x6c
	v_bitop3_b32 v31, v4, 64, v5 bitop3:0x6c
	v_bitop3_b32 v32, v4, 32, v5 bitop3:0x6c
	v_bitop3_b32 v33, v4, 16, v5 bitop3:0x6c
	v_bitop3_b32 v34, v4, 8, v5 bitop3:0x6c
	v_bitop3_b32 v35, v4, 4, v5 bitop3:0x6c
	s_waitcnt lgkmcnt(0)
	v_lshl_add_u64 v[4:5], s[6:7], 0, v[0:1]
	s_lshl_b32 s6, s0, 3
	v_or_b32_e32 v6, 0x400, v0
	v_or_b32_e32 v8, 0x800, v0
	v_or_b32_e32 v0, 0xc00, v0
	s_ashr_i32 s5, s4, 31
	v_mov_b32_e32 v7, v1
	v_mov_b32_e32 v9, v1
	v_lshl_add_u64 v[10:11], s[8:9], 0, v[0:1]
	s_ashr_i32 s7, s6, 31
	s_lshl_b64 s[0:1], s[4:5], 11
	v_and_b32_e32 v0, 63, v12
	v_lshl_add_u64 v[6:7], s[8:9], 0, v[6:7]
	v_lshl_add_u64 v[8:9], s[8:9], 0, v[8:9]
	s_lshl_b64 s[8:9], s[4:5], 7
	s_lshl_b64 s[10:11], s[6:7], 7
	v_lshl_or_b32 v12, v0, 3, s0
	v_mov_b32_e32 v13, s1
	s_lshl_b64 s[12:13], s[6:7], 11
	v_mov_b32_e32 v0, 0x34ff7000
	v_mov_b32_e32 v36, 0x358637bd
	s_mov_b32 s18, 0x800000
	v_lshlrev_b32_e32 v37, 2, v14
	global_load_dwordx4 v[100:103], v[4:5], off
	global_load_dwordx4 v[104:107], v[4:5], off offset:1024
	global_load_dwordx4 v[108:111], v[4:5], off offset:2048
	global_load_dwordx4 v[112:115], v[4:5], off offset:3072
	s_cmpk_lt_i32 s4, 0x4000
	s_cbranch_scc0 .LBB0_4349
